# GEMM loops: scalar pointer/counter bookkeeping moved off the post-barrier head of load phases (after DMA issue / into MFMA tail)
# speedup vs baseline: 1.0013x; 1.0013x over previous
; #define PG8_STAGE(bufoff, gbase, voff) do { _Pragma("unroll") for (int _i = 0; _i < 2; ++_i) \
;         __builtin_amdgcn_global_load_lds((const unsigned*)((const char*)(gbase) + (voff)[_i]), (PG8_LAS unsigned*)(lds + (bufoff) + ldsw + _i * 8192), 16, 0, 0); } while (0)
; #define PG8_LDA(dst, b, h) do { _Pragma("unroll") for (int m = 0; m < 4; ++m) _Pragma("unroll") for (int k = 0; k < 2; ++k) dst[m][k] = *(const PG8_LAS bf16x8*)(lds + PG8_SA(b, h) + aoff + m * 2048 + k * 1024); } while (0)
; #define PG8_LDB(dst, b, h) do { _Pragma("unroll") for (int n = 0; n < 2; ++n) _Pragma("unroll") for (int k = 0; k < 2; ++k) dst[n][k] = *(const PG8_LAS bf16x8*)(lds + PG8_SB(b, h) + boff + n * 2048 + k * 1024); } while (0)
; #define PG8_MMA(ai, bj, At, Bt) do { __builtin_amdgcn_s_setprio(1); _Pragma("unroll") for (int m = 0; m < 4; ++m) _Pragma("unroll") for (int n = 0; n < 2; ++n) _Pragma("unroll") for (int k = 0; k < 2; ++k) \
;         acc[ai][bj][m][n] = __builtin_amdgcn_mfma_f32_16x16x32_bf16(Bt[n][k], At[m][k], acc[ai][bj][m][n], 0, 0, 0); __builtin_amdgcn_s_setprio(0); } while (0)
; #define PG8_WAIT_V(n) asm volatile("s_waitcnt vmcnt(" #n ")" ::: "memory")
; #define PG8_WAIT_L(n) asm volatile("s_waitcnt lgkmcnt(" #n ")" ::: "memory")
; template <class Epi, class Sched, bool ALIGN_EPI = false, bool SP2 = false>
; __device__ __forceinline__ void gemm_phase(PG8_LAS unsigned char* lds, const Gemm g, const Sched& S, const Epi& E) {
;     ...
;             const bool last = (t == nt - 2);
;             const char* a1 = cA + (size_t)(t + 1) * kstep;
;             const char* a2 = last ? nA : cA + (size_t)(t + 2) * kstep; const char* b2 = last ? nB : cB + (size_t)(t + 2) * kstep;
;             const char* a3 = a2 + kstep; const char* b3 = b2 + kstep;
;             if (last && has_next) S.a_ready(nxt);
;             if constexpr (SP2) {
;             PG8_LDB(B0, 0, 0); PG8_LDB(B1, 0, 1); PG8_SCHED; PG8_LDA(At, 0, 0); PG8_STAGE(PG8_SA(1, 1), a1 + hstep, voffA);
;             PG8_WAIT_V(8); PG8_WAIT_L(0); PG8_BAR; PG8_MMA(0, 0, At, B0); PG8_MMA(0, 1, At, B1); PG8_BAR; PG8_SCHED;
;             PG8_LDA(At, 0, 1); PG8_STAGE(PG8_SB(0, 0), b2, voffB); PG8_STAGE(PG8_SB(0, 1), b2 + hstep, voffB); PG8_STAGE(PG8_SA(0, 0), a2, voffA);
;             PG8_WAIT_V(8); PG8_WAIT_L(0); PG8_BAR; PG8_MMA(1, 0, At, B0); PG8_MMA(1, 1, At, B1); PG8_BAR; PG8_SCHED;
.LBB0_165:
	ds_read_b128 v[130:133], v161
	ds_read_b128 v[146:149], v161 offset:1024
	ds_read_b128 v[150:153], v161 offset:2048
	ds_read_b128 v[154:157], v161 offset:3072
	ds_read_b128 v[180:183], v161 offset:16384
	ds_read_b128 v[184:187], v161 offset:17408
	ds_read_b128 v[188:191], v161 offset:18432
	ds_read_b128 v[192:195], v161 offset:19456
	s_add_i32 m0, s45, 0xc000
	ds_read_b128 v[196:199], v164
	ds_read_b128 v[200:203], v164 offset:1024
	ds_read_b128 v[218:221], v164 offset:2048
	ds_read_b128 v[222:225], v164 offset:3072
	ds_read_b128 v[226:229], v164 offset:4096
	ds_read_b128 v[230:233], v164 offset:5120
	ds_read_b128 v[234:237], v164 offset:6144
	ds_read_b128 v[238:241], v164 offset:7168
	global_load_lds_dwordx4 v142, s[26:27]
	s_add_i32 m0, s45, 0xe000
	s_nop 0
	global_load_lds_dwordx4 v144, s[26:27]
	s_add_u32 s28, s26, 0xfff80080
	s_addc_u32 s29, s27, -1
	s_add_i32 s78, 0, 0x10000
	s_cmp_eq_u32 s77, 28
	s_cselect_b32 s41, s17, s29
	s_cselect_b32 s40, s25, s28
	s_cselect_b32 s29, s23, s73
	s_cselect_b32 s28, s54, s55
	s_add_i32 s80, 0, 0x14000
	s_waitcnt vmcnt(8)
	s_waitcnt lgkmcnt(0)
	s_barrier
	v_mfma_f32_16x16x32_bf16 v[126:129], v[130:133], v[196:199], v[126:129]
	v_mfma_f32_16x16x32_bf16 v[118:121], v[150:153], v[196:199], v[118:121]
	v_mfma_f32_16x16x32_bf16 v[110:113], v[130:133], v[218:221], v[110:113]
	v_mfma_f32_16x16x32_bf16 v[102:105], v[150:153], v[218:221], v[102:105]
	v_mfma_f32_16x16x32_bf16 v[94:97], v[130:133], v[226:229], v[94:97]
	v_mfma_f32_16x16x32_bf16 v[86:89], v[150:153], v[226:229], v[86:89]
	v_mfma_f32_16x16x32_bf16 v[78:81], v[130:133], v[234:237], v[78:81]
	v_mfma_f32_16x16x32_bf16 v[70:73], v[150:153], v[234:237], v[70:73]
	v_mfma_f32_16x16x32_bf16 v[126:129], v[146:149], v[200:203], v[126:129]
	v_mfma_f32_16x16x32_bf16 v[118:121], v[154:157], v[200:203], v[118:121]
	v_mfma_f32_16x16x32_bf16 v[110:113], v[146:149], v[222:225], v[110:113]
	v_mfma_f32_16x16x32_bf16 v[102:105], v[154:157], v[222:225], v[102:105]
	v_mfma_f32_16x16x32_bf16 v[94:97], v[146:149], v[230:233], v[94:97]
	v_mfma_f32_16x16x32_bf16 v[86:89], v[154:157], v[230:233], v[86:89]
	v_mfma_f32_16x16x32_bf16 v[78:81], v[146:149], v[238:241], v[78:81]
	v_mfma_f32_16x16x32_bf16 v[70:73], v[154:157], v[238:241], v[70:73]
	v_mfma_f32_16x16x32_bf16 v[122:125], v[180:183], v[196:199], v[122:125]
	v_mfma_f32_16x16x32_bf16 v[114:117], v[188:191], v[196:199], v[114:117]
	v_mfma_f32_16x16x32_bf16 v[106:109], v[180:183], v[218:221], v[106:109]
	v_mfma_f32_16x16x32_bf16 v[98:101], v[188:191], v[218:221], v[98:101]
	v_mfma_f32_16x16x32_bf16 v[90:93], v[180:183], v[226:229], v[90:93]
	v_mfma_f32_16x16x32_bf16 v[82:85], v[188:191], v[226:229], v[82:85]
	v_mfma_f32_16x16x32_bf16 v[74:77], v[180:183], v[234:237], v[74:77]
	v_mfma_f32_16x16x32_bf16 v[66:69], v[188:191], v[234:237], v[66:69]
	v_mfma_f32_16x16x32_bf16 v[122:125], v[184:187], v[200:203], v[122:125]
	v_mfma_f32_16x16x32_bf16 v[114:117], v[192:195], v[200:203], v[114:117]
	v_mfma_f32_16x16x32_bf16 v[106:109], v[184:187], v[222:225], v[106:109]
	v_mfma_f32_16x16x32_bf16 v[98:101], v[192:195], v[222:225], v[98:101]
	v_mfma_f32_16x16x32_bf16 v[90:93], v[184:187], v[230:233], v[90:93]
	v_mfma_f32_16x16x32_bf16 v[82:85], v[192:195], v[230:233], v[82:85]
	v_mfma_f32_16x16x32_bf16 v[74:77], v[184:187], v[238:241], v[74:77]
	v_mfma_f32_16x16x32_bf16 v[66:69], v[192:195], v[238:241], v[66:69]
	s_barrier
	ds_read_b128 v[196:199], v164 offset:16384
	ds_read_b128 v[200:203], v164 offset:17408
	ds_read_b128 v[218:221], v164 offset:18432
	ds_read_b128 v[222:225], v164 offset:19456
	ds_read_b128 v[226:229], v164 offset:20480
	ds_read_b128 v[230:233], v164 offset:21504
	ds_read_b128 v[234:237], v164 offset:22528
	ds_read_b128 v[238:241], v164 offset:23552
	s_add_i32 s78, s78, s46
	s_mov_b32 m0, s78
	s_nop 0
	global_load_lds_dwordx4 v0, s[28:29]
	s_add_i32 m0, s78, 0x2000
	s_add_u32 vcc_lo, s28, 0x80000
	v_lshl_add_u64 v[166:167], s[28:29], 0, v[134:135]
	s_addc_u32 vcc_hi, s29, 0
	s_add_i32 s78, s80, s46
	global_load_lds_dwordx4 v134, s[28:29]
	s_mov_b32 m0, s78
	v_lshl_add_u64 v[244:245], s[40:41], 0, v[136:137]
	global_load_lds_dwordx4 v0, vcc
	s_add_i32 m0, s78, 0x2000
	s_nop 0
	global_load_lds_dwordx4 v134, vcc
	v_lshl_add_u64 v[242:243], s[40:41], 0, v[138:139]
	s_mov_b32 m0, s45
	s_nop 0
	global_load_lds_dwordx4 v138, s[40:41]
	s_mov_b32 m0, s49
	s_nop 0
	global_load_lds_dwordx4 v136, s[40:41]
	s_waitcnt vmcnt(8)
	s_waitcnt lgkmcnt(0)
	s_barrier
	v_mfma_f32_16x16x32_bf16 v[62:65], v[130:133], v[196:199], v[62:65]
	v_mfma_f32_16x16x32_bf16 v[54:57], v[150:153], v[196:199], v[54:57]
	v_mfma_f32_16x16x32_bf16 v[46:49], v[130:133], v[218:221], v[46:49]
	v_mfma_f32_16x16x32_bf16 v[38:41], v[150:153], v[218:221], v[38:41]
	v_mfma_f32_16x16x32_bf16 v[30:33], v[130:133], v[226:229], v[30:33]
	v_mfma_f32_16x16x32_bf16 v[22:25], v[150:153], v[226:229], v[22:25]
	v_mfma_f32_16x16x32_bf16 v[14:17], v[130:133], v[234:237], v[14:17]
	v_mfma_f32_16x16x32_bf16 v[6:9], v[150:153], v[234:237], v[6:9]
	v_mfma_f32_16x16x32_bf16 v[62:65], v[146:149], v[200:203], v[62:65]
	v_mfma_f32_16x16x32_bf16 v[54:57], v[154:157], v[200:203], v[54:57]
	v_mfma_f32_16x16x32_bf16 v[46:49], v[146:149], v[222:225], v[46:49]
	v_mfma_f32_16x16x32_bf16 v[38:41], v[154:157], v[222:225], v[38:41]
	v_mfma_f32_16x16x32_bf16 v[30:33], v[146:149], v[230:233], v[30:33]
	v_mfma_f32_16x16x32_bf16 v[22:25], v[154:157], v[230:233], v[22:25]
	v_mfma_f32_16x16x32_bf16 v[14:17], v[146:149], v[238:241], v[14:17]
	v_mfma_f32_16x16x32_bf16 v[6:9], v[154:157], v[238:241], v[6:9]
	v_mfma_f32_16x16x32_bf16 v[58:61], v[180:183], v[196:199], v[58:61]
	v_mfma_f32_16x16x32_bf16 v[50:53], v[188:191], v[196:199], v[50:53]
	v_mfma_f32_16x16x32_bf16 v[42:45], v[180:183], v[218:221], v[42:45]
	v_mfma_f32_16x16x32_bf16 v[34:37], v[188:191], v[218:221], v[34:37]
	v_mfma_f32_16x16x32_bf16 v[26:29], v[180:183], v[226:229], v[26:29]
	v_mfma_f32_16x16x32_bf16 v[18:21], v[188:191], v[226:229], v[18:21]
	v_mfma_f32_16x16x32_bf16 v[10:13], v[180:183], v[234:237], v[10:13]
	v_mfma_f32_16x16x32_bf16 v[2:5], v[188:191], v[234:237], v[2:5]
	v_mfma_f32_16x16x32_bf16 v[58:61], v[184:187], v[200:203], v[58:61]
	v_mfma_f32_16x16x32_bf16 v[50:53], v[192:195], v[200:203], v[50:53]
	v_mfma_f32_16x16x32_bf16 v[42:45], v[184:187], v[222:225], v[42:45]
	v_mfma_f32_16x16x32_bf16 v[34:37], v[192:195], v[222:225], v[34:37]
	v_mfma_f32_16x16x32_bf16 v[26:29], v[184:187], v[230:233], v[26:29]
	v_mfma_f32_16x16x32_bf16 v[18:21], v[192:195], v[230:233], v[18:21]
	v_mfma_f32_16x16x32_bf16 v[10:13], v[184:187], v[238:241], v[10:13]
	v_mfma_f32_16x16x32_bf16 v[2:5], v[192:195], v[238:241], v[2:5]
	s_barrier
; #define PG8_STAGE(bufoff, gbase, voff) do { _Pragma("unroll") for (int _i = 0; _i < 2; ++_i) \
;         __builtin_amdgcn_global_load_lds((const unsigned*)((const char*)(gbase) + (voff)[_i]), (PG8_LAS unsigned*)(lds + (bufoff) + ldsw + _i * 8192), 16, 0, 0); } while (0)
; #define PG8_LDA(dst, b, h) do { _Pragma("unroll") for (int m = 0; m < 4; ++m) _Pragma("unroll") for (int k = 0; k < 2; ++k) dst[m][k] = *(const PG8_LAS bf16x8*)(lds + PG8_SA(b, h) + aoff + m * 2048 + k * 1024); } while (0)
; #define PG8_LDB(dst, b, h) do { _Pragma("unroll") for (int n = 0; n < 2; ++n) _Pragma("unroll") for (int k = 0; k < 2; ++k) dst[n][k] = *(const PG8_LAS bf16x8*)(lds + PG8_SB(b, h) + boff + n * 2048 + k * 1024); } while (0)
; #define PG8_MMA(ai, bj, At, Bt) do { __builtin_amdgcn_s_setprio(1); _Pragma("unroll") for (int m = 0; m < 4; ++m) _Pragma("unroll") for (int n = 0; n < 2; ++n) _Pragma("unroll") for (int k = 0; k < 2; ++k) \
;         acc[ai][bj][m][n] = __builtin_amdgcn_mfma_f32_16x16x32_bf16(Bt[n][k], At[m][k], acc[ai][bj][m][n], 0, 0, 0); __builtin_amdgcn_s_setprio(0); } while (0)
; #define PG8_WAIT_V(n) asm volatile("s_waitcnt vmcnt(" #n ")" ::: "memory")
; #define PG8_WAIT_L(n) asm volatile("s_waitcnt lgkmcnt(" #n ")" ::: "memory")
; #define PG8_BAR __builtin_amdgcn_s_barrier()
; #define PG8_SCHED __builtin_amdgcn_sched_barrier(0)
; template <class Epi, class Sched, bool ALIGN_EPI = false, bool SP2 = false>
; __device__ __forceinline__ void gemm_phase(PG8_LAS unsigned char* lds, const Gemm g, const Sched& S, const Epi& E) {
;     ...
;             PG8_LDB(B0, 1, 0); PG8_LDB(B1, 1, 1); PG8_SCHED; PG8_LDA(At, 1, 0); PG8_STAGE(PG8_SA(0, 1), a2 + hstep, voffA);
;             PG8_WAIT_V(8); PG8_WAIT_L(0); PG8_BAR; PG8_MMA(0, 0, At, B0); PG8_MMA(0, 1, At, B1); PG8_BAR; PG8_SCHED;
;             PG8_LDA(At, 1, 1); PG8_STAGE(PG8_SB(1, 0), b3, voffB); PG8_STAGE(PG8_SB(1, 1), b3 + hstep, voffB); PG8_STAGE(PG8_SA(1, 0), a3, voffA);
;             PG8_WAIT_V(8); PG8_WAIT_L(0); PG8_BAR; PG8_MMA(1, 0, At, B0); PG8_MMA(1, 1, At, B1); PG8_BAR; PG8_SCHED;
	ds_read_b128 v[130:133], v161 offset:32768
	ds_read_b128 v[146:149], v161 offset:33792
	ds_read_b128 v[150:153], v161 offset:34816
	ds_read_b128 v[154:157], v161 offset:35840
	ds_read_b128 v[180:183], v161 offset:49152
	ds_read_b128 v[184:187], v161 offset:50176
	ds_read_b128 v[188:191], v161 offset:51200
	ds_read_b128 v[192:195], v161 offset:52224
	s_add_i32 s78, 0, 0x18000
	s_add_i32 s80, 0, 0x1c000
	s_add_u32 s40, s40, 0x80000
	s_addc_u32 s41, s41, 0
	s_mov_b32 m0, s50
	ds_read_b128 v[196:199], v164 offset:32768
	ds_read_b128 v[200:203], v164 offset:33792
	ds_read_b128 v[218:221], v164 offset:34816
	ds_read_b128 v[222:225], v164 offset:35840
	ds_read_b128 v[226:229], v164 offset:36864
	ds_read_b128 v[230:233], v164 offset:37888
	ds_read_b128 v[234:237], v164 offset:38912
	ds_read_b128 v[238:241], v164 offset:39936
	global_load_lds_dwordx4 v138, s[40:41]
	s_mov_b32 m0, s51
	s_nop 0
	global_load_lds_dwordx4 v136, s[40:41]
	s_waitcnt vmcnt(8)
	s_waitcnt lgkmcnt(0)
	s_barrier
	v_mfma_f32_16x16x32_bf16 v[126:129], v[130:133], v[196:199], v[126:129]
	v_mfma_f32_16x16x32_bf16 v[118:121], v[150:153], v[196:199], v[118:121]
	v_mfma_f32_16x16x32_bf16 v[110:113], v[130:133], v[218:221], v[110:113]
	v_mfma_f32_16x16x32_bf16 v[102:105], v[150:153], v[218:221], v[102:105]
	v_mfma_f32_16x16x32_bf16 v[94:97], v[130:133], v[226:229], v[94:97]
	v_mfma_f32_16x16x32_bf16 v[86:89], v[150:153], v[226:229], v[86:89]
	v_mfma_f32_16x16x32_bf16 v[78:81], v[130:133], v[234:237], v[78:81]
	v_mfma_f32_16x16x32_bf16 v[70:73], v[150:153], v[234:237], v[70:73]
	v_mfma_f32_16x16x32_bf16 v[126:129], v[146:149], v[200:203], v[126:129]
	v_mfma_f32_16x16x32_bf16 v[118:121], v[154:157], v[200:203], v[118:121]
	v_mfma_f32_16x16x32_bf16 v[110:113], v[146:149], v[222:225], v[110:113]
	v_mfma_f32_16x16x32_bf16 v[102:105], v[154:157], v[222:225], v[102:105]
	v_mfma_f32_16x16x32_bf16 v[94:97], v[146:149], v[230:233], v[94:97]
	v_mfma_f32_16x16x32_bf16 v[86:89], v[154:157], v[230:233], v[86:89]
	v_mfma_f32_16x16x32_bf16 v[78:81], v[146:149], v[238:241], v[78:81]
	v_mfma_f32_16x16x32_bf16 v[70:73], v[154:157], v[238:241], v[70:73]
	v_mfma_f32_16x16x32_bf16 v[122:125], v[180:183], v[196:199], v[122:125]
	v_mfma_f32_16x16x32_bf16 v[114:117], v[188:191], v[196:199], v[114:117]
	v_mfma_f32_16x16x32_bf16 v[106:109], v[180:183], v[218:221], v[106:109]
	v_mfma_f32_16x16x32_bf16 v[98:101], v[188:191], v[218:221], v[98:101]
	v_mfma_f32_16x16x32_bf16 v[90:93], v[180:183], v[226:229], v[90:93]
	v_mfma_f32_16x16x32_bf16 v[82:85], v[188:191], v[226:229], v[82:85]
	v_mfma_f32_16x16x32_bf16 v[74:77], v[180:183], v[234:237], v[74:77]
	v_mfma_f32_16x16x32_bf16 v[66:69], v[188:191], v[234:237], v[66:69]
	v_mfma_f32_16x16x32_bf16 v[122:125], v[184:187], v[200:203], v[122:125]
	v_mfma_f32_16x16x32_bf16 v[114:117], v[192:195], v[200:203], v[114:117]
	v_mfma_f32_16x16x32_bf16 v[106:109], v[184:187], v[222:225], v[106:109]
	v_mfma_f32_16x16x32_bf16 v[98:101], v[192:195], v[222:225], v[98:101]
	v_mfma_f32_16x16x32_bf16 v[90:93], v[184:187], v[230:233], v[90:93]
	v_mfma_f32_16x16x32_bf16 v[82:85], v[192:195], v[230:233], v[82:85]
	v_mfma_f32_16x16x32_bf16 v[74:77], v[184:187], v[238:241], v[74:77]
	v_mfma_f32_16x16x32_bf16 v[66:69], v[192:195], v[238:241], v[66:69]
	s_barrier
	ds_read_b128 v[196:199], v164 offset:49152
	ds_read_b128 v[200:203], v164 offset:50176
	ds_read_b128 v[218:221], v164 offset:51200
	ds_read_b128 v[222:225], v164 offset:52224
	ds_read_b128 v[226:229], v164 offset:53248
	ds_read_b128 v[230:233], v164 offset:54272
	ds_read_b128 v[234:237], v164 offset:55296
	ds_read_b128 v[238:241], v164 offset:56320
	s_add_i32 s40, s78, s46
	s_add_i32 m0, s40, 0xffffff80
	s_nop 0
	global_load_lds_dwordx4 v0, s[28:29] offset:128
	s_add_i32 m0, s40, 0x2000
	s_add_u32 s28, s28, 0x80080
	v_lshl_add_u64 v[158:159], v[166:167], 0, s[34:35]
	s_addc_u32 s29, s29, 0
	s_add_i32 s40, s80, s46
	global_load_lds_dwordx4 v[158:159], off
	s_mov_b32 m0, s40
	s_nop 0
	global_load_lds_dwordx4 v0, s[28:29]
	s_add_i32 m0, s40, 0x2000
	s_nop 0
	global_load_lds_dwordx4 v134, s[28:29]
	v_lshl_add_u64 v[158:159], v[242:243], 0, s[34:35]
	s_mov_b32 m0, s4
	s_nop 0
	global_load_lds_dwordx4 v[158:159], off
	v_lshl_add_u64 v[158:159], v[244:245], 0, s[34:35]
	s_mov_b32 m0, s52
	s_nop 0
	global_load_lds_dwordx4 v[158:159], off
	s_waitcnt vmcnt(8)
	s_waitcnt lgkmcnt(0)
	s_barrier
	v_mfma_f32_16x16x32_bf16 v[62:65], v[130:133], v[196:199], v[62:65]
	v_mfma_f32_16x16x32_bf16 v[54:57], v[150:153], v[196:199], v[54:57]
	v_mfma_f32_16x16x32_bf16 v[46:49], v[130:133], v[218:221], v[46:49]
	v_mfma_f32_16x16x32_bf16 v[38:41], v[150:153], v[218:221], v[38:41]
	v_mfma_f32_16x16x32_bf16 v[30:33], v[130:133], v[226:229], v[30:33]
	v_mfma_f32_16x16x32_bf16 v[22:25], v[150:153], v[226:229], v[22:25]
	v_mfma_f32_16x16x32_bf16 v[14:17], v[130:133], v[234:237], v[14:17]
	v_mfma_f32_16x16x32_bf16 v[6:9], v[150:153], v[234:237], v[6:9]
	v_mfma_f32_16x16x32_bf16 v[62:65], v[146:149], v[200:203], v[62:65]
	v_mfma_f32_16x16x32_bf16 v[54:57], v[154:157], v[200:203], v[54:57]
	v_mfma_f32_16x16x32_bf16 v[46:49], v[146:149], v[222:225], v[46:49]
	v_mfma_f32_16x16x32_bf16 v[38:41], v[154:157], v[222:225], v[38:41]
	v_mfma_f32_16x16x32_bf16 v[30:33], v[146:149], v[230:233], v[30:33]
	v_mfma_f32_16x16x32_bf16 v[22:25], v[154:157], v[230:233], v[22:25]
	v_mfma_f32_16x16x32_bf16 v[14:17], v[146:149], v[238:241], v[14:17]
	v_mfma_f32_16x16x32_bf16 v[6:9], v[154:157], v[238:241], v[6:9]
	v_mfma_f32_16x16x32_bf16 v[58:61], v[180:183], v[196:199], v[58:61]
	v_mfma_f32_16x16x32_bf16 v[50:53], v[188:191], v[196:199], v[50:53]
	v_mfma_f32_16x16x32_bf16 v[42:45], v[180:183], v[218:221], v[42:45]
	v_mfma_f32_16x16x32_bf16 v[34:37], v[188:191], v[218:221], v[34:37]
	v_mfma_f32_16x16x32_bf16 v[26:29], v[180:183], v[226:229], v[26:29]
	v_mfma_f32_16x16x32_bf16 v[18:21], v[188:191], v[226:229], v[18:21]
	v_mfma_f32_16x16x32_bf16 v[10:13], v[180:183], v[234:237], v[10:13]
	v_mfma_f32_16x16x32_bf16 v[2:5], v[188:191], v[234:237], v[2:5]
	v_mfma_f32_16x16x32_bf16 v[58:61], v[184:187], v[200:203], v[58:61]
	v_mfma_f32_16x16x32_bf16 v[50:53], v[192:195], v[200:203], v[50:53]
	s_add_i32 s77, s77, 2
	v_mfma_f32_16x16x32_bf16 v[42:45], v[184:187], v[222:225], v[42:45]
	s_add_u32 s26, s26, 0x100
	v_mfma_f32_16x16x32_bf16 v[34:37], v[192:195], v[222:225], v[34:37]
	s_addc_u32 s27, s27, 0
	v_mfma_f32_16x16x32_bf16 v[26:29], v[184:187], v[230:233], v[26:29]
	s_add_u32 s55, s55, 0x100
	v_mfma_f32_16x16x32_bf16 v[18:21], v[192:195], v[230:233], v[18:21]
	s_addc_u32 s73, s73, 0
	v_mfma_f32_16x16x32_bf16 v[10:13], v[184:187], v[238:241], v[10:13]
	v_mfma_f32_16x16x32_bf16 v[2:5], v[192:195], v[238:241], v[2:5]
	s_barrier
	s_cmp_gt_u32 s77, 29
	s_cbranch_scc0 .LBB0_165
	s_and_b64 vcc, exec, s[20:21]
	s_cbranch_vccz .LBB0_168
	s_barrier

; #define PG8_STAGE(bufoff, gbase, voff) do { _Pragma("unroll") for (int _i = 0; _i < 2; ++_i) \
;         __builtin_amdgcn_global_load_lds((const unsigned*)((const char*)(gbase) + (voff)[_i]), (PG8_LAS unsigned*)(lds + (bufoff) + ldsw + _i * 8192), 16, 0, 0); } while (0)
; #define PG8_LDA(dst, b, h) do { _Pragma("unroll") for (int m = 0; m < 4; ++m) _Pragma("unroll") for (int k = 0; k < 2; ++k) dst[m][k] = *(const PG8_LAS bf16x8*)(lds + PG8_SA(b, h) + aoff + m * 2048 + k * 1024); } while (0)
; #define PG8_LDB(dst, b, h) do { _Pragma("unroll") for (int n = 0; n < 2; ++n) _Pragma("unroll") for (int k = 0; k < 2; ++k) dst[n][k] = *(const PG8_LAS bf16x8*)(lds + PG8_SB(b, h) + boff + n * 2048 + k * 1024); } while (0)
; #define PG8_MMA(ai, bj, At, Bt) do { __builtin_amdgcn_s_setprio(1); _Pragma("unroll") for (int m = 0; m < 4; ++m) _Pragma("unroll") for (int n = 0; n < 2; ++n) _Pragma("unroll") for (int k = 0; k < 2; ++k) \
;         acc[ai][bj][m][n] = __builtin_amdgcn_mfma_f32_16x16x32_bf16(Bt[n][k], At[m][k], acc[ai][bj][m][n], 0, 0, 0); __builtin_amdgcn_s_setprio(0); } while (0)
; #define PG8_WAIT_V(n) asm volatile("s_waitcnt vmcnt(" #n ")" ::: "memory")
; #define PG8_WAIT_L(n) asm volatile("s_waitcnt lgkmcnt(" #n ")" ::: "memory")
; template <class Epi, class Sched, bool ALIGN_EPI = false, bool SP2 = false>
; __device__ __forceinline__ void gemm_phase(PG8_LAS unsigned char* lds, const Gemm g, const Sched& S, const Epi& E) {
;     ...
;             const bool last = (t == nt - 2);
;             const char* a1 = cA + (size_t)(t + 1) * kstep;
;             const char* a2 = last ? nA : cA + (size_t)(t + 2) * kstep; const char* b2 = last ? nB : cB + (size_t)(t + 2) * kstep;
;             const char* a3 = a2 + kstep; const char* b3 = b2 + kstep;
;             if (last && has_next) S.a_ready(nxt);
;             if constexpr (SP2) {
;             PG8_LDB(B0, 0, 0); PG8_LDB(B1, 0, 1); PG8_SCHED; PG8_LDA(At, 0, 0); PG8_STAGE(PG8_SA(1, 1), a1 + hstep, voffA);
;             PG8_WAIT_V(8); PG8_WAIT_L(0); PG8_BAR; PG8_MMA(0, 0, At, B0); PG8_MMA(0, 1, At, B1); PG8_BAR; PG8_SCHED;
;             PG8_LDA(At, 0, 1); PG8_STAGE(PG8_SB(0, 0), b2, voffB); PG8_STAGE(PG8_SB(0, 1), b2 + hstep, voffB); PG8_STAGE(PG8_SA(0, 0), a2, voffA);
;             PG8_WAIT_V(8); PG8_WAIT_L(0); PG8_BAR; PG8_MMA(1, 0, At, B0); PG8_MMA(1, 1, At, B1); PG8_BAR; PG8_SCHED;
.LBB0_429:
	ds_read_b128 v[52:55], v218
	ds_read_b128 v[56:59], v218 offset:1024
	ds_read_b128 v[92:95], v218 offset:2048
	ds_read_b128 v[96:99], v218 offset:3072
	ds_read_b128 v[124:127], v218 offset:16384
	ds_read_b128 v[128:131], v218 offset:17408
	ds_read_b128 v[148:151], v218 offset:18432
	ds_read_b128 v[152:155], v218 offset:19456
	s_add_i32 m0, s37, 0xc000
	ds_read_b128 v[164:167], v220
	ds_read_b128 v[192:195], v220 offset:1024
	ds_read_b128 v[196:199], v220 offset:2048
	ds_read_b128 v[200:203], v220 offset:3072
	ds_read_b128 v[222:225], v220 offset:4096
	ds_read_b128 v[226:229], v220 offset:5120
	ds_read_b128 v[230:233], v220 offset:6144
	ds_read_b128 v[234:237], v220 offset:7168
	global_load_lds_dwordx4 v188, s[16:17]
	s_add_i32 m0, s37, 0xe000
	s_nop 0
	global_load_lds_dwordx4 v190, s[16:17]
	s_add_u32 s26, s16, 0xfffc0080
	s_addc_u32 s27, s17, -1
	s_add_i32 s54, 0, 0x10000
	s_cmp_eq_u32 s78, 12
	s_cselect_b32 s29, s21, s27
	s_cselect_b32 s28, s52, s26
	s_cselect_b32 s27, s19, s77
	s_cselect_b32 s26, s53, s73
	s_add_i32 s55, 0, 0x14000
	s_waitcnt vmcnt(8)
	s_waitcnt lgkmcnt(0)
	s_barrier
	v_mfma_f32_16x16x32_bf16 v[88:91], v[52:55], v[164:167], v[88:91]
	v_mfma_f32_16x16x32_bf16 v[84:87], v[92:95], v[164:167], v[84:87]
	v_mfma_f32_16x16x32_bf16 v[120:123], v[52:55], v[196:199], v[120:123]
	v_mfma_f32_16x16x32_bf16 v[108:111], v[92:95], v[196:199], v[108:111]
	v_mfma_f32_16x16x32_bf16 v[136:139], v[52:55], v[222:225], v[136:139]
	v_mfma_f32_16x16x32_bf16 v[132:135], v[92:95], v[222:225], v[132:135]
	v_mfma_f32_16x16x32_bf16 v[104:107], v[52:55], v[230:233], v[104:107]
	v_mfma_f32_16x16x32_bf16 v[100:103], v[92:95], v[230:233], v[100:103]
	v_mfma_f32_16x16x32_bf16 v[88:91], v[56:59], v[192:195], v[88:91]
	v_mfma_f32_16x16x32_bf16 v[84:87], v[96:99], v[192:195], v[84:87]
	v_mfma_f32_16x16x32_bf16 v[120:123], v[56:59], v[200:203], v[120:123]
	v_mfma_f32_16x16x32_bf16 v[108:111], v[96:99], v[200:203], v[108:111]
	v_mfma_f32_16x16x32_bf16 v[136:139], v[56:59], v[226:229], v[136:139]
	v_mfma_f32_16x16x32_bf16 v[132:135], v[96:99], v[226:229], v[132:135]
	v_mfma_f32_16x16x32_bf16 v[104:107], v[56:59], v[234:237], v[104:107]
	v_mfma_f32_16x16x32_bf16 v[100:103], v[96:99], v[234:237], v[100:103]
	v_mfma_f32_16x16x32_bf16 v[160:163], v[124:127], v[164:167], v[160:163]
	v_mfma_f32_16x16x32_bf16 v[156:159], v[148:151], v[164:167], v[156:159]
	v_mfma_f32_16x16x32_bf16 v[144:147], v[124:127], v[196:199], v[144:147]
	v_mfma_f32_16x16x32_bf16 v[140:143], v[148:151], v[196:199], v[140:143]
	v_mfma_f32_16x16x32_bf16 v[116:119], v[124:127], v[222:225], v[116:119]
	v_mfma_f32_16x16x32_bf16 v[112:115], v[148:151], v[222:225], v[112:115]
	v_mfma_f32_16x16x32_bf16 v[80:83], v[124:127], v[230:233], v[80:83]
	v_mfma_f32_16x16x32_bf16 v[76:79], v[148:151], v[230:233], v[76:79]
	v_mfma_f32_16x16x32_bf16 v[160:163], v[128:131], v[192:195], v[160:163]
	v_mfma_f32_16x16x32_bf16 v[156:159], v[152:155], v[192:195], v[156:159]
	v_mfma_f32_16x16x32_bf16 v[144:147], v[128:131], v[200:203], v[144:147]
	v_mfma_f32_16x16x32_bf16 v[140:143], v[152:155], v[200:203], v[140:143]
	v_mfma_f32_16x16x32_bf16 v[116:119], v[128:131], v[226:229], v[116:119]
	v_mfma_f32_16x16x32_bf16 v[112:115], v[152:155], v[226:229], v[112:115]
	v_mfma_f32_16x16x32_bf16 v[80:83], v[128:131], v[234:237], v[80:83]
	v_mfma_f32_16x16x32_bf16 v[76:79], v[152:155], v[234:237], v[76:79]
	s_barrier
	ds_read_b128 v[164:167], v220 offset:16384
	ds_read_b128 v[192:195], v220 offset:17408
	ds_read_b128 v[196:199], v220 offset:18432
	ds_read_b128 v[200:203], v220 offset:19456
	ds_read_b128 v[222:225], v220 offset:20480
	ds_read_b128 v[226:229], v220 offset:21504
	ds_read_b128 v[230:233], v220 offset:22528
	ds_read_b128 v[234:237], v220 offset:23552
	s_add_i32 s54, s54, s2
	s_mov_b32 m0, s54
	s_nop 0
	global_load_lds_dwordx4 v184, s[26:27]
	s_add_i32 m0, s54, 0x2000
	s_add_u32 vcc_lo, s26, 0x40000
	v_lshl_add_u64 v[240:241], s[26:27], 0, v[180:181]
	s_addc_u32 vcc_hi, s27, 0
	s_add_i32 s54, s55, s2
	global_load_lds_dwordx4 v180, s[26:27]
	s_mov_b32 m0, s54
	v_lshl_add_u64 v[242:243], s[28:29], 0, v[186:187]
	global_load_lds_dwordx4 v184, vcc
	s_add_i32 m0, s54, 0x2000
	v_lshl_add_u64 v[244:245], s[28:29], 0, v[182:183]
	global_load_lds_dwordx4 v180, vcc
	s_mov_b32 m0, s37
	s_nop 0
	global_load_lds_dwordx4 v186, s[28:29]
	s_mov_b32 m0, s38
	s_nop 0
	global_load_lds_dwordx4 v182, s[28:29]
	s_waitcnt vmcnt(8)
	s_waitcnt lgkmcnt(0)
	s_barrier
	v_mfma_f32_16x16x32_bf16 v[72:75], v[52:55], v[164:167], v[72:75]
	v_mfma_f32_16x16x32_bf16 v[68:71], v[92:95], v[164:167], v[68:71]
	v_mfma_f32_16x16x32_bf16 v[48:51], v[52:55], v[196:199], v[48:51]
	v_mfma_f32_16x16x32_bf16 v[44:47], v[92:95], v[196:199], v[44:47]
	v_mfma_f32_16x16x32_bf16 v[32:35], v[52:55], v[222:225], v[32:35]
	v_mfma_f32_16x16x32_bf16 v[28:31], v[92:95], v[222:225], v[28:31]
	v_mfma_f32_16x16x32_bf16 v[16:19], v[52:55], v[230:233], v[16:19]
	v_mfma_f32_16x16x32_bf16 v[12:15], v[92:95], v[230:233], v[12:15]
	v_mfma_f32_16x16x32_bf16 v[72:75], v[56:59], v[192:195], v[72:75]
	v_mfma_f32_16x16x32_bf16 v[68:71], v[96:99], v[192:195], v[68:71]
	v_mfma_f32_16x16x32_bf16 v[48:51], v[56:59], v[200:203], v[48:51]
	v_mfma_f32_16x16x32_bf16 v[44:47], v[96:99], v[200:203], v[44:47]
	v_mfma_f32_16x16x32_bf16 v[32:35], v[56:59], v[226:229], v[32:35]
	v_mfma_f32_16x16x32_bf16 v[28:31], v[96:99], v[226:229], v[28:31]
	v_mfma_f32_16x16x32_bf16 v[16:19], v[56:59], v[234:237], v[16:19]
	v_mfma_f32_16x16x32_bf16 v[12:15], v[96:99], v[234:237], v[12:15]
	v_mfma_f32_16x16x32_bf16 v[40:43], v[124:127], v[196:199], v[40:43]
	v_mfma_f32_16x16x32_bf16 v[36:39], v[148:151], v[196:199], v[36:39]
	v_mfma_f32_16x16x32_bf16 v[24:27], v[124:127], v[222:225], v[24:27]
	v_mfma_f32_16x16x32_bf16 v[20:23], v[148:151], v[222:225], v[20:23]
	v_mfma_f32_16x16x32_bf16 v[8:11], v[124:127], v[230:233], v[8:11]
	v_mfma_f32_16x16x32_bf16 v[2:5], v[148:151], v[230:233], v[4:7]
	v_mfma_f32_16x16x32_bf16 v[52:55], v[124:127], v[164:167], v[64:67]
	v_mfma_f32_16x16x32_bf16 v[56:59], v[148:151], v[164:167], v[60:63]
	v_mfma_f32_16x16x32_bf16 v[40:43], v[128:131], v[200:203], v[40:43]
	v_mfma_f32_16x16x32_bf16 v[36:39], v[152:155], v[200:203], v[36:39]
	v_mfma_f32_16x16x32_bf16 v[24:27], v[128:131], v[226:229], v[24:27]
	v_mfma_f32_16x16x32_bf16 v[20:23], v[152:155], v[226:229], v[20:23]
	v_mfma_f32_16x16x32_bf16 v[8:11], v[128:131], v[234:237], v[8:11]
	v_mfma_f32_16x16x32_bf16 v[2:5], v[152:155], v[234:237], v[2:5]
	v_mfma_f32_16x16x32_bf16 v[52:55], v[128:131], v[192:195], v[52:55]
	v_mfma_f32_16x16x32_bf16 v[56:59], v[152:155], v[192:195], v[56:59]
	s_barrier
; #define PG8_STAGE(bufoff, gbase, voff) do { _Pragma("unroll") for (int _i = 0; _i < 2; ++_i) \
;         __builtin_amdgcn_global_load_lds((const unsigned*)((const char*)(gbase) + (voff)[_i]), (PG8_LAS unsigned*)(lds + (bufoff) + ldsw + _i * 8192), 16, 0, 0); } while (0)
; #define PG8_LDA(dst, b, h) do { _Pragma("unroll") for (int m = 0; m < 4; ++m) _Pragma("unroll") for (int k = 0; k < 2; ++k) dst[m][k] = *(const PG8_LAS bf16x8*)(lds + PG8_SA(b, h) + aoff + m * 2048 + k * 1024); } while (0)
; #define PG8_LDB(dst, b, h) do { _Pragma("unroll") for (int n = 0; n < 2; ++n) _Pragma("unroll") for (int k = 0; k < 2; ++k) dst[n][k] = *(const PG8_LAS bf16x8*)(lds + PG8_SB(b, h) + boff + n * 2048 + k * 1024); } while (0)
; #define PG8_MMA(ai, bj, At, Bt) do { __builtin_amdgcn_s_setprio(1); _Pragma("unroll") for (int m = 0; m < 4; ++m) _Pragma("unroll") for (int n = 0; n < 2; ++n) _Pragma("unroll") for (int k = 0; k < 2; ++k) \
;         acc[ai][bj][m][n] = __builtin_amdgcn_mfma_f32_16x16x32_bf16(Bt[n][k], At[m][k], acc[ai][bj][m][n], 0, 0, 0); __builtin_amdgcn_s_setprio(0); } while (0)
; #define PG8_WAIT_V(n) asm volatile("s_waitcnt vmcnt(" #n ")" ::: "memory")
; #define PG8_WAIT_L(n) asm volatile("s_waitcnt lgkmcnt(" #n ")" ::: "memory")
; #define PG8_BAR __builtin_amdgcn_s_barrier()
; #define PG8_SCHED __builtin_amdgcn_sched_barrier(0)
; template <class Epi, class Sched, bool ALIGN_EPI = false, bool SP2 = false>
; __device__ __forceinline__ void gemm_phase(PG8_LAS unsigned char* lds, const Gemm g, const Sched& S, const Epi& E) {
;     ...
;             PG8_LDB(B0, 1, 0); PG8_LDB(B1, 1, 1); PG8_SCHED; PG8_LDA(At, 1, 0); PG8_STAGE(PG8_SA(0, 1), a2 + hstep, voffA);
;             PG8_WAIT_V(8); PG8_WAIT_L(0); PG8_BAR; PG8_MMA(0, 0, At, B0); PG8_MMA(0, 1, At, B1); PG8_BAR; PG8_SCHED;
;             PG8_LDA(At, 1, 1); PG8_STAGE(PG8_SB(1, 0), b3, voffB); PG8_STAGE(PG8_SB(1, 1), b3 + hstep, voffB); PG8_STAGE(PG8_SA(1, 0), a3, voffA);
;             PG8_WAIT_V(8); PG8_WAIT_L(0); PG8_BAR; PG8_MMA(1, 0, At, B0); PG8_MMA(1, 1, At, B1); PG8_BAR; PG8_SCHED;
	ds_read_b128 v[60:63], v218 offset:32768
	ds_read_b128 v[64:67], v218 offset:33792
	ds_read_b128 v[92:95], v218 offset:34816
	ds_read_b128 v[96:99], v218 offset:35840
	ds_read_b128 v[124:127], v218 offset:49152
	ds_read_b128 v[128:131], v218 offset:50176
	ds_read_b128 v[148:151], v218 offset:51200
	ds_read_b128 v[152:155], v218 offset:52224
	s_add_i32 s54, 0, 0x18000
	s_add_i32 s55, 0, 0x1c000
	s_add_u32 s28, s28, 0x40000
	s_addc_u32 s29, s29, 0
	s_mov_b32 m0, s39
	ds_read_b128 v[164:167], v220 offset:32768
	ds_read_b128 v[192:195], v220 offset:33792
	ds_read_b128 v[196:199], v220 offset:34816
	ds_read_b128 v[200:203], v220 offset:35840
	ds_read_b128 v[222:225], v220 offset:36864
	ds_read_b128 v[226:229], v220 offset:37888
	ds_read_b128 v[230:233], v220 offset:38912
	ds_read_b128 v[234:237], v220 offset:39936
	global_load_lds_dwordx4 v186, s[28:29]
	s_mov_b32 m0, s44
	s_nop 0
	global_load_lds_dwordx4 v182, s[28:29]
	s_waitcnt vmcnt(8)
	s_waitcnt lgkmcnt(0)
	s_barrier
	v_mfma_f32_16x16x32_bf16 v[88:91], v[60:63], v[164:167], v[88:91]
	v_mfma_f32_16x16x32_bf16 v[84:87], v[92:95], v[164:167], v[84:87]
	v_mfma_f32_16x16x32_bf16 v[120:123], v[60:63], v[196:199], v[120:123]
	v_mfma_f32_16x16x32_bf16 v[108:111], v[92:95], v[196:199], v[108:111]
	v_mfma_f32_16x16x32_bf16 v[136:139], v[60:63], v[222:225], v[136:139]
	v_mfma_f32_16x16x32_bf16 v[132:135], v[92:95], v[222:225], v[132:135]
	v_mfma_f32_16x16x32_bf16 v[104:107], v[60:63], v[230:233], v[104:107]
	v_mfma_f32_16x16x32_bf16 v[100:103], v[92:95], v[230:233], v[100:103]
	v_mfma_f32_16x16x32_bf16 v[88:91], v[64:67], v[192:195], v[88:91]
	v_mfma_f32_16x16x32_bf16 v[84:87], v[96:99], v[192:195], v[84:87]
	v_mfma_f32_16x16x32_bf16 v[120:123], v[64:67], v[200:203], v[120:123]
	v_mfma_f32_16x16x32_bf16 v[108:111], v[96:99], v[200:203], v[108:111]
	v_mfma_f32_16x16x32_bf16 v[136:139], v[64:67], v[226:229], v[136:139]
	v_mfma_f32_16x16x32_bf16 v[132:135], v[96:99], v[226:229], v[132:135]
	v_mfma_f32_16x16x32_bf16 v[104:107], v[64:67], v[234:237], v[104:107]
	v_mfma_f32_16x16x32_bf16 v[100:103], v[96:99], v[234:237], v[100:103]
	v_mfma_f32_16x16x32_bf16 v[160:163], v[124:127], v[164:167], v[160:163]
	v_mfma_f32_16x16x32_bf16 v[156:159], v[148:151], v[164:167], v[156:159]
	v_mfma_f32_16x16x32_bf16 v[144:147], v[124:127], v[196:199], v[144:147]
	v_mfma_f32_16x16x32_bf16 v[140:143], v[148:151], v[196:199], v[140:143]
	v_mfma_f32_16x16x32_bf16 v[116:119], v[124:127], v[222:225], v[116:119]
	v_mfma_f32_16x16x32_bf16 v[112:115], v[148:151], v[222:225], v[112:115]
	v_mfma_f32_16x16x32_bf16 v[80:83], v[124:127], v[230:233], v[80:83]
	v_mfma_f32_16x16x32_bf16 v[76:79], v[148:151], v[230:233], v[76:79]
	v_mfma_f32_16x16x32_bf16 v[160:163], v[128:131], v[192:195], v[160:163]
	v_mfma_f32_16x16x32_bf16 v[156:159], v[152:155], v[192:195], v[156:159]
	v_mfma_f32_16x16x32_bf16 v[144:147], v[128:131], v[200:203], v[144:147]
	v_mfma_f32_16x16x32_bf16 v[140:143], v[152:155], v[200:203], v[140:143]
	v_mfma_f32_16x16x32_bf16 v[116:119], v[128:131], v[226:229], v[116:119]
	v_mfma_f32_16x16x32_bf16 v[112:115], v[152:155], v[226:229], v[112:115]
	v_mfma_f32_16x16x32_bf16 v[80:83], v[128:131], v[234:237], v[80:83]
	v_mfma_f32_16x16x32_bf16 v[76:79], v[152:155], v[234:237], v[76:79]
	s_barrier
	ds_read_b128 v[164:167], v220 offset:49152
	ds_read_b128 v[192:195], v220 offset:50176
	ds_read_b128 v[196:199], v220 offset:51200
	ds_read_b128 v[200:203], v220 offset:52224
	ds_read_b128 v[222:225], v220 offset:53248
	ds_read_b128 v[226:229], v220 offset:54272
	ds_read_b128 v[230:233], v220 offset:55296
	ds_read_b128 v[234:237], v220 offset:56320
	s_add_i32 s28, s54, s2
	s_add_i32 m0, s28, 0xffffff80
	s_nop 0
	global_load_lds_dwordx4 v184, s[26:27] offset:128
	s_add_i32 m0, s28, 0x2000
	s_add_u32 s26, s26, 0x40080
	v_lshl_add_u64 v[6:7], v[240:241], 0, s[34:35]
	s_addc_u32 s27, s27, 0
	s_add_i32 s28, s55, s2
	global_load_lds_dwordx4 v[6:7], off
	s_mov_b32 m0, s28
	s_nop 0
	global_load_lds_dwordx4 v184, s[26:27]
	s_add_i32 m0, s28, 0x2000
	s_nop 0
	global_load_lds_dwordx4 v180, s[26:27]
	v_lshl_add_u64 v[6:7], v[242:243], 0, s[34:35]
	s_mov_b32 m0, s47
	s_nop 0
	global_load_lds_dwordx4 v[6:7], off
	v_lshl_add_u64 v[6:7], v[244:245], 0, s[34:35]
	s_mov_b32 m0, s48
	s_nop 0
	global_load_lds_dwordx4 v[6:7], off
	s_waitcnt vmcnt(8)
	s_waitcnt lgkmcnt(0)
	s_barrier
	v_mfma_f32_16x16x32_bf16 v[72:75], v[60:63], v[164:167], v[72:75]
	v_mfma_f32_16x16x32_bf16 v[68:71], v[92:95], v[164:167], v[68:71]
	v_mfma_f32_16x16x32_bf16 v[48:51], v[60:63], v[196:199], v[48:51]
	v_mfma_f32_16x16x32_bf16 v[44:47], v[92:95], v[196:199], v[44:47]
	v_mfma_f32_16x16x32_bf16 v[32:35], v[60:63], v[222:225], v[32:35]
	v_mfma_f32_16x16x32_bf16 v[28:31], v[92:95], v[222:225], v[28:31]
	v_mfma_f32_16x16x32_bf16 v[16:19], v[60:63], v[230:233], v[16:19]
	v_mfma_f32_16x16x32_bf16 v[12:15], v[92:95], v[230:233], v[12:15]
	v_mfma_f32_16x16x32_bf16 v[72:75], v[64:67], v[192:195], v[72:75]
	v_mfma_f32_16x16x32_bf16 v[68:71], v[96:99], v[192:195], v[68:71]
	v_mfma_f32_16x16x32_bf16 v[48:51], v[64:67], v[200:203], v[48:51]
	v_mfma_f32_16x16x32_bf16 v[44:47], v[96:99], v[200:203], v[44:47]
	v_mfma_f32_16x16x32_bf16 v[32:35], v[64:67], v[226:229], v[32:35]
	v_mfma_f32_16x16x32_bf16 v[28:31], v[96:99], v[226:229], v[28:31]
	v_mfma_f32_16x16x32_bf16 v[16:19], v[64:67], v[234:237], v[16:19]
	v_mfma_f32_16x16x32_bf16 v[12:15], v[96:99], v[234:237], v[12:15]
	v_mfma_f32_16x16x32_bf16 v[52:55], v[124:127], v[164:167], v[52:55]
	v_mfma_f32_16x16x32_bf16 v[64:67], v[128:131], v[192:195], v[52:55]
	v_mfma_f32_16x16x32_bf16 v[52:55], v[148:151], v[164:167], v[56:59]
	v_mfma_f32_16x16x32_bf16 v[40:43], v[124:127], v[196:199], v[40:43]
	v_mfma_f32_16x16x32_bf16 v[36:39], v[148:151], v[196:199], v[36:39]
	v_mfma_f32_16x16x32_bf16 v[24:27], v[124:127], v[222:225], v[24:27]
	v_mfma_f32_16x16x32_bf16 v[20:23], v[148:151], v[222:225], v[20:23]
	v_mfma_f32_16x16x32_bf16 v[6:9], v[124:127], v[230:233], v[8:11]
	v_mfma_f32_16x16x32_bf16 v[2:5], v[148:151], v[230:233], v[2:5]
	v_mfma_f32_16x16x32_bf16 v[60:63], v[152:155], v[192:195], v[52:55]
	s_add_i32 s78, s78, 2
	v_mfma_f32_16x16x32_bf16 v[40:43], v[128:131], v[200:203], v[40:43]
	s_add_u32 s16, s16, 0x100
	v_mfma_f32_16x16x32_bf16 v[36:39], v[152:155], v[200:203], v[36:39]
	s_addc_u32 s17, s17, 0
	v_mfma_f32_16x16x32_bf16 v[24:27], v[128:131], v[226:229], v[24:27]
	s_add_u32 s73, s73, 0x100
	v_mfma_f32_16x16x32_bf16 v[20:23], v[152:155], v[226:229], v[20:23]
	s_addc_u32 s77, s77, 0
	v_mfma_f32_16x16x32_bf16 v[8:11], v[128:131], v[234:237], v[6:9]
	v_mfma_f32_16x16x32_bf16 v[4:7], v[152:155], v[234:237], v[2:5]
	s_barrier
	s_cmp_gt_u32 s78, 13
	s_cbranch_scc0 .LBB0_429
	s_and_b64 vcc, exec, s[6:7]
	s_cbranch_vccz .LBB0_432
	s_barrier

; #define PG8_STAGE(bufoff, gbase, voff) do { _Pragma("unroll") for (int _i = 0; _i < 2; ++_i) \
;         __builtin_amdgcn_global_load_lds((const unsigned*)((const char*)(gbase) + (voff)[_i]), (PG8_LAS unsigned*)(lds + (bufoff) + ldsw + _i * 8192), 16, 0, 0); } while (0)
; #define PG8_LDA(dst, b, h) do { _Pragma("unroll") for (int m = 0; m < 4; ++m) _Pragma("unroll") for (int k = 0; k < 2; ++k) dst[m][k] = *(const PG8_LAS bf16x8*)(lds + PG8_SA(b, h) + aoff + m * 2048 + k * 1024); } while (0)
; #define PG8_LDB(dst, b, h) do { _Pragma("unroll") for (int n = 0; n < 2; ++n) _Pragma("unroll") for (int k = 0; k < 2; ++k) dst[n][k] = *(const PG8_LAS bf16x8*)(lds + PG8_SB(b, h) + boff + n * 2048 + k * 1024); } while (0)
; #define PG8_MMA(ai, bj, At, Bt) do { __builtin_amdgcn_s_setprio(1); _Pragma("unroll") for (int m = 0; m < 4; ++m) _Pragma("unroll") for (int n = 0; n < 2; ++n) _Pragma("unroll") for (int k = 0; k < 2; ++k) \
;         acc[ai][bj][m][n] = __builtin_amdgcn_mfma_f32_16x16x32_bf16(Bt[n][k], At[m][k], acc[ai][bj][m][n], 0, 0, 0); __builtin_amdgcn_s_setprio(0); } while (0)
; #define PG8_WAIT_V(n) asm volatile("s_waitcnt vmcnt(" #n ")" ::: "memory")
; #define PG8_WAIT_L(n) asm volatile("s_waitcnt lgkmcnt(" #n ")" ::: "memory")
; template <class Epi, class Sched, bool ALIGN_EPI = false, bool SP2 = false>
; __device__ __forceinline__ void gemm_phase(PG8_LAS unsigned char* lds, const Gemm g, const Sched& S, const Epi& E) {
;     ...
;             const bool last = (t == nt - 2);
;             const char* a1 = cA + (size_t)(t + 1) * kstep;
;             const char* a2 = last ? nA : cA + (size_t)(t + 2) * kstep; const char* b2 = last ? nB : cB + (size_t)(t + 2) * kstep;
;             const char* a3 = a2 + kstep; const char* b3 = b2 + kstep;
;             if (last && has_next) S.a_ready(nxt);
;             if constexpr (SP2) {
;             PG8_LDB(B0, 0, 0); PG8_LDB(B1, 0, 1); PG8_SCHED; PG8_LDA(At, 0, 0); PG8_STAGE(PG8_SA(1, 1), a1 + hstep, voffA);
;             PG8_WAIT_V(8); PG8_WAIT_L(0); PG8_BAR; PG8_MMA(0, 0, At, B0); PG8_MMA(0, 1, At, B1); PG8_BAR; PG8_SCHED;
;             PG8_LDA(At, 0, 1); PG8_STAGE(PG8_SB(0, 0), b2, voffB); PG8_STAGE(PG8_SB(0, 1), b2 + hstep, voffB); PG8_STAGE(PG8_SA(0, 0), a2, voffA);
;             PG8_WAIT_V(8); PG8_WAIT_L(0); PG8_BAR; PG8_MMA(1, 0, At, B0); PG8_MMA(1, 1, At, B1); PG8_BAR; PG8_SCHED;
.LBB0_553:
	ds_read_b128 v[114:117], v191
	ds_read_b128 v[118:121], v191 offset:1024
	ds_read_b128 v[122:125], v191 offset:2048
	ds_read_b128 v[134:137], v191 offset:3072
	ds_read_b128 v[146:149], v191 offset:16384
	ds_read_b128 v[150:153], v191 offset:17408
	ds_read_b128 v[180:183], v191 offset:18432
	ds_read_b128 v[184:187], v191 offset:19456
	s_add_i32 m0, s48, 0xc000
	ds_read_b128 v[196:199], v194
	ds_read_b128 v[200:203], v194 offset:1024
	ds_read_b128 v[218:221], v194 offset:2048
	ds_read_b128 v[222:225], v194 offset:3072
	ds_read_b128 v[226:229], v194 offset:4096
	ds_read_b128 v[230:233], v194 offset:5120
	ds_read_b128 v[234:237], v194 offset:6144
	ds_read_b128 v[238:241], v194 offset:7168
	global_load_lds_dwordx4 v162, s[16:17]
	s_add_i32 m0, s48, 0xe000
	s_nop 0
	global_load_lds_dwordx4 v164, s[16:17]
	s_add_u32 s26, s16, 0xfff80080
	s_addc_u32 s27, s17, -1
	s_add_i32 s54, 0, 0x10000
	s_cmp_eq_u32 vcc_hi, 28
	s_cselect_b32 s29, s23, s27
	s_cselect_b32 s28, s38, s26
	s_cselect_b32 s27, s21, vcc_lo
	s_cselect_b32 s26, s39, s78
	s_add_i32 s80, 0, 0x14000
	s_waitcnt vmcnt(8)
	s_waitcnt lgkmcnt(0)
	s_barrier
	v_mfma_f32_16x16x32_bf16 v[142:145], v[114:117], v[196:199], v[142:145]
	v_mfma_f32_16x16x32_bf16 v[138:141], v[122:125], v[196:199], v[138:141]
	v_mfma_f32_16x16x32_bf16 v[110:113], v[114:117], v[218:221], v[110:113]
	v_mfma_f32_16x16x32_bf16 v[106:109], v[122:125], v[218:221], v[106:109]
	v_mfma_f32_16x16x32_bf16 v[94:97], v[114:117], v[226:229], v[94:97]
	v_mfma_f32_16x16x32_bf16 v[90:93], v[122:125], v[226:229], v[90:93]
	v_mfma_f32_16x16x32_bf16 v[78:81], v[114:117], v[234:237], v[78:81]
	v_mfma_f32_16x16x32_bf16 v[74:77], v[122:125], v[234:237], v[74:77]
	v_mfma_f32_16x16x32_bf16 v[142:145], v[118:121], v[200:203], v[142:145]
	v_mfma_f32_16x16x32_bf16 v[138:141], v[134:137], v[200:203], v[138:141]
	v_mfma_f32_16x16x32_bf16 v[110:113], v[118:121], v[222:225], v[110:113]
	v_mfma_f32_16x16x32_bf16 v[106:109], v[134:137], v[222:225], v[106:109]
	v_mfma_f32_16x16x32_bf16 v[94:97], v[118:121], v[230:233], v[94:97]
	v_mfma_f32_16x16x32_bf16 v[90:93], v[134:137], v[230:233], v[90:93]
	v_mfma_f32_16x16x32_bf16 v[78:81], v[118:121], v[238:241], v[78:81]
	v_mfma_f32_16x16x32_bf16 v[74:77], v[134:137], v[238:241], v[74:77]
	v_mfma_f32_16x16x32_bf16 v[130:133], v[146:149], v[196:199], v[130:133]
	v_mfma_f32_16x16x32_bf16 v[126:129], v[180:183], v[196:199], v[126:129]
	v_mfma_f32_16x16x32_bf16 v[102:105], v[146:149], v[218:221], v[102:105]
	v_mfma_f32_16x16x32_bf16 v[98:101], v[180:183], v[218:221], v[98:101]
	v_mfma_f32_16x16x32_bf16 v[86:89], v[146:149], v[226:229], v[86:89]
	v_mfma_f32_16x16x32_bf16 v[82:85], v[180:183], v[226:229], v[82:85]
	v_mfma_f32_16x16x32_bf16 v[70:73], v[146:149], v[234:237], v[70:73]
	v_mfma_f32_16x16x32_bf16 v[66:69], v[180:183], v[234:237], v[66:69]
	v_mfma_f32_16x16x32_bf16 v[130:133], v[150:153], v[200:203], v[130:133]
	v_mfma_f32_16x16x32_bf16 v[126:129], v[184:187], v[200:203], v[126:129]
	v_mfma_f32_16x16x32_bf16 v[102:105], v[150:153], v[222:225], v[102:105]
	v_mfma_f32_16x16x32_bf16 v[98:101], v[184:187], v[222:225], v[98:101]
	v_mfma_f32_16x16x32_bf16 v[86:89], v[150:153], v[230:233], v[86:89]
	v_mfma_f32_16x16x32_bf16 v[82:85], v[184:187], v[230:233], v[82:85]
	v_mfma_f32_16x16x32_bf16 v[70:73], v[150:153], v[238:241], v[70:73]
	v_mfma_f32_16x16x32_bf16 v[66:69], v[184:187], v[238:241], v[66:69]
	s_barrier
	ds_read_b128 v[196:199], v194 offset:16384
	ds_read_b128 v[200:203], v194 offset:17408
	ds_read_b128 v[218:221], v194 offset:18432
	ds_read_b128 v[222:225], v194 offset:19456
	ds_read_b128 v[226:229], v194 offset:20480
	ds_read_b128 v[230:233], v194 offset:21504
	ds_read_b128 v[234:237], v194 offset:22528
	ds_read_b128 v[238:241], v194 offset:23552
	s_add_i32 s54, s54, s2
	s_mov_b32 m0, s54
	s_nop 0
	global_load_lds_dwordx4 v0, s[26:27]
	s_add_i32 m0, s54, 0x2000
	s_add_u32 s54, s26, 0x80000
	v_lshl_add_u64 v[188:189], s[26:27], 0, v[154:155]
	s_addc_u32 s55, s27, 0
	s_add_i32 s80, s80, s2
	global_load_lds_dwordx4 v154, s[26:27]
	s_mov_b32 m0, s80
	v_lshl_add_u64 v[244:245], s[28:29], 0, v[156:157]
	global_load_lds_dwordx4 v0, s[54:55]
	s_add_i32 m0, s80, 0x2000
	s_nop 0
	global_load_lds_dwordx4 v154, s[54:55]
	v_lshl_add_u64 v[242:243], s[28:29], 0, v[158:159]
	s_mov_b32 m0, s48
	s_nop 0
	global_load_lds_dwordx4 v158, s[28:29]
	s_mov_b32 m0, s49
	s_nop 0
	global_load_lds_dwordx4 v156, s[28:29]
	s_waitcnt vmcnt(8)
	s_waitcnt lgkmcnt(0)
	s_barrier
	v_mfma_f32_16x16x32_bf16 v[62:65], v[114:117], v[196:199], v[62:65]
	v_mfma_f32_16x16x32_bf16 v[58:61], v[122:125], v[196:199], v[58:61]
	v_mfma_f32_16x16x32_bf16 v[46:49], v[114:117], v[218:221], v[46:49]
	v_mfma_f32_16x16x32_bf16 v[42:45], v[122:125], v[218:221], v[42:45]
	v_mfma_f32_16x16x32_bf16 v[30:33], v[114:117], v[226:229], v[30:33]
	v_mfma_f32_16x16x32_bf16 v[26:29], v[122:125], v[226:229], v[26:29]
	v_mfma_f32_16x16x32_bf16 v[14:17], v[114:117], v[234:237], v[14:17]
	v_mfma_f32_16x16x32_bf16 v[10:13], v[122:125], v[234:237], v[10:13]
	v_mfma_f32_16x16x32_bf16 v[62:65], v[118:121], v[200:203], v[62:65]
	v_mfma_f32_16x16x32_bf16 v[58:61], v[134:137], v[200:203], v[58:61]
	v_mfma_f32_16x16x32_bf16 v[46:49], v[118:121], v[222:225], v[46:49]
	v_mfma_f32_16x16x32_bf16 v[42:45], v[134:137], v[222:225], v[42:45]
	v_mfma_f32_16x16x32_bf16 v[30:33], v[118:121], v[230:233], v[30:33]
	v_mfma_f32_16x16x32_bf16 v[26:29], v[134:137], v[230:233], v[26:29]
	v_mfma_f32_16x16x32_bf16 v[14:17], v[118:121], v[238:241], v[14:17]
	v_mfma_f32_16x16x32_bf16 v[10:13], v[134:137], v[238:241], v[10:13]
	v_mfma_f32_16x16x32_bf16 v[54:57], v[146:149], v[196:199], v[54:57]
	v_mfma_f32_16x16x32_bf16 v[50:53], v[180:183], v[196:199], v[50:53]
	v_mfma_f32_16x16x32_bf16 v[38:41], v[146:149], v[218:221], v[38:41]
	v_mfma_f32_16x16x32_bf16 v[34:37], v[180:183], v[218:221], v[34:37]
	v_mfma_f32_16x16x32_bf16 v[22:25], v[146:149], v[226:229], v[22:25]
	v_mfma_f32_16x16x32_bf16 v[18:21], v[180:183], v[226:229], v[18:21]
	v_mfma_f32_16x16x32_bf16 v[6:9], v[146:149], v[234:237], v[6:9]
	v_mfma_f32_16x16x32_bf16 v[2:5], v[180:183], v[234:237], v[2:5]
	v_mfma_f32_16x16x32_bf16 v[54:57], v[150:153], v[200:203], v[54:57]
	v_mfma_f32_16x16x32_bf16 v[50:53], v[184:187], v[200:203], v[50:53]
	v_mfma_f32_16x16x32_bf16 v[38:41], v[150:153], v[222:225], v[38:41]
	v_mfma_f32_16x16x32_bf16 v[34:37], v[184:187], v[222:225], v[34:37]
	v_mfma_f32_16x16x32_bf16 v[22:25], v[150:153], v[230:233], v[22:25]
	v_mfma_f32_16x16x32_bf16 v[18:21], v[184:187], v[230:233], v[18:21]
	v_mfma_f32_16x16x32_bf16 v[6:9], v[150:153], v[238:241], v[6:9]
	v_mfma_f32_16x16x32_bf16 v[2:5], v[184:187], v[238:241], v[2:5]
	s_barrier
; #define PG8_STAGE(bufoff, gbase, voff) do { _Pragma("unroll") for (int _i = 0; _i < 2; ++_i) \
;         __builtin_amdgcn_global_load_lds((const unsigned*)((const char*)(gbase) + (voff)[_i]), (PG8_LAS unsigned*)(lds + (bufoff) + ldsw + _i * 8192), 16, 0, 0); } while (0)
; #define PG8_LDA(dst, b, h) do { _Pragma("unroll") for (int m = 0; m < 4; ++m) _Pragma("unroll") for (int k = 0; k < 2; ++k) dst[m][k] = *(const PG8_LAS bf16x8*)(lds + PG8_SA(b, h) + aoff + m * 2048 + k * 1024); } while (0)
; #define PG8_LDB(dst, b, h) do { _Pragma("unroll") for (int n = 0; n < 2; ++n) _Pragma("unroll") for (int k = 0; k < 2; ++k) dst[n][k] = *(const PG8_LAS bf16x8*)(lds + PG8_SB(b, h) + boff + n * 2048 + k * 1024); } while (0)
; #define PG8_MMA(ai, bj, At, Bt) do { __builtin_amdgcn_s_setprio(1); _Pragma("unroll") for (int m = 0; m < 4; ++m) _Pragma("unroll") for (int n = 0; n < 2; ++n) _Pragma("unroll") for (int k = 0; k < 2; ++k) \
;         acc[ai][bj][m][n] = __builtin_amdgcn_mfma_f32_16x16x32_bf16(Bt[n][k], At[m][k], acc[ai][bj][m][n], 0, 0, 0); __builtin_amdgcn_s_setprio(0); } while (0)
; #define PG8_WAIT_V(n) asm volatile("s_waitcnt vmcnt(" #n ")" ::: "memory")
; #define PG8_WAIT_L(n) asm volatile("s_waitcnt lgkmcnt(" #n ")" ::: "memory")
; #define PG8_BAR __builtin_amdgcn_s_barrier()
; #define PG8_SCHED __builtin_amdgcn_sched_barrier(0)
; template <class Epi, class Sched, bool ALIGN_EPI = false, bool SP2 = false>
; __device__ __forceinline__ void gemm_phase(PG8_LAS unsigned char* lds, const Gemm g, const Sched& S, const Epi& E) {
;     ...
;             PG8_LDB(B0, 1, 0); PG8_LDB(B1, 1, 1); PG8_SCHED; PG8_LDA(At, 1, 0); PG8_STAGE(PG8_SA(0, 1), a2 + hstep, voffA);
;             PG8_WAIT_V(8); PG8_WAIT_L(0); PG8_BAR; PG8_MMA(0, 0, At, B0); PG8_MMA(0, 1, At, B1); PG8_BAR; PG8_SCHED;
;             PG8_LDA(At, 1, 1); PG8_STAGE(PG8_SB(1, 0), b3, voffB); PG8_STAGE(PG8_SB(1, 1), b3 + hstep, voffB); PG8_STAGE(PG8_SA(1, 0), a3, voffA);
;             PG8_WAIT_V(8); PG8_WAIT_L(0); PG8_BAR; PG8_MMA(1, 0, At, B0); PG8_MMA(1, 1, At, B1); PG8_BAR; PG8_SCHED;
	ds_read_b128 v[114:117], v191 offset:32768
	ds_read_b128 v[118:121], v191 offset:33792
	ds_read_b128 v[122:125], v191 offset:34816
	ds_read_b128 v[134:137], v191 offset:35840
	ds_read_b128 v[146:149], v191 offset:49152
	ds_read_b128 v[150:153], v191 offset:50176
	ds_read_b128 v[180:183], v191 offset:51200
	ds_read_b128 v[184:187], v191 offset:52224
	s_add_i32 s54, 0, 0x18000
	s_add_i32 s55, 0, 0x1c000
	s_add_u32 s28, s28, 0x80000
	s_addc_u32 s29, s29, 0
	s_mov_b32 m0, s50
	ds_read_b128 v[196:199], v194 offset:32768
	ds_read_b128 v[200:203], v194 offset:33792
	ds_read_b128 v[218:221], v194 offset:34816
	ds_read_b128 v[222:225], v194 offset:35840
	ds_read_b128 v[226:229], v194 offset:36864
	ds_read_b128 v[230:233], v194 offset:37888
	ds_read_b128 v[234:237], v194 offset:38912
	ds_read_b128 v[238:241], v194 offset:39936
	global_load_lds_dwordx4 v158, s[28:29]
	s_mov_b32 m0, s51
	s_nop 0
	global_load_lds_dwordx4 v156, s[28:29]
	s_waitcnt vmcnt(8)
	s_waitcnt lgkmcnt(0)
	s_barrier
	v_mfma_f32_16x16x32_bf16 v[142:145], v[114:117], v[196:199], v[142:145]
	v_mfma_f32_16x16x32_bf16 v[138:141], v[122:125], v[196:199], v[138:141]
	v_mfma_f32_16x16x32_bf16 v[110:113], v[114:117], v[218:221], v[110:113]
	v_mfma_f32_16x16x32_bf16 v[106:109], v[122:125], v[218:221], v[106:109]
	v_mfma_f32_16x16x32_bf16 v[94:97], v[114:117], v[226:229], v[94:97]
	v_mfma_f32_16x16x32_bf16 v[90:93], v[122:125], v[226:229], v[90:93]
	v_mfma_f32_16x16x32_bf16 v[78:81], v[114:117], v[234:237], v[78:81]
	v_mfma_f32_16x16x32_bf16 v[74:77], v[122:125], v[234:237], v[74:77]
	v_mfma_f32_16x16x32_bf16 v[142:145], v[118:121], v[200:203], v[142:145]
	v_mfma_f32_16x16x32_bf16 v[138:141], v[134:137], v[200:203], v[138:141]
	v_mfma_f32_16x16x32_bf16 v[110:113], v[118:121], v[222:225], v[110:113]
	v_mfma_f32_16x16x32_bf16 v[106:109], v[134:137], v[222:225], v[106:109]
	v_mfma_f32_16x16x32_bf16 v[94:97], v[118:121], v[230:233], v[94:97]
	v_mfma_f32_16x16x32_bf16 v[90:93], v[134:137], v[230:233], v[90:93]
	v_mfma_f32_16x16x32_bf16 v[78:81], v[118:121], v[238:241], v[78:81]
	v_mfma_f32_16x16x32_bf16 v[74:77], v[134:137], v[238:241], v[74:77]
	v_mfma_f32_16x16x32_bf16 v[130:133], v[146:149], v[196:199], v[130:133]
	v_mfma_f32_16x16x32_bf16 v[126:129], v[180:183], v[196:199], v[126:129]
	v_mfma_f32_16x16x32_bf16 v[102:105], v[146:149], v[218:221], v[102:105]
	v_mfma_f32_16x16x32_bf16 v[98:101], v[180:183], v[218:221], v[98:101]
	v_mfma_f32_16x16x32_bf16 v[86:89], v[146:149], v[226:229], v[86:89]
	v_mfma_f32_16x16x32_bf16 v[82:85], v[180:183], v[226:229], v[82:85]
	v_mfma_f32_16x16x32_bf16 v[70:73], v[146:149], v[234:237], v[70:73]
	v_mfma_f32_16x16x32_bf16 v[66:69], v[180:183], v[234:237], v[66:69]
	v_mfma_f32_16x16x32_bf16 v[130:133], v[150:153], v[200:203], v[130:133]
	v_mfma_f32_16x16x32_bf16 v[126:129], v[184:187], v[200:203], v[126:129]
	v_mfma_f32_16x16x32_bf16 v[102:105], v[150:153], v[222:225], v[102:105]
	v_mfma_f32_16x16x32_bf16 v[98:101], v[184:187], v[222:225], v[98:101]
	v_mfma_f32_16x16x32_bf16 v[86:89], v[150:153], v[230:233], v[86:89]
	v_mfma_f32_16x16x32_bf16 v[82:85], v[184:187], v[230:233], v[82:85]
	v_mfma_f32_16x16x32_bf16 v[70:73], v[150:153], v[238:241], v[70:73]
	v_mfma_f32_16x16x32_bf16 v[66:69], v[184:187], v[238:241], v[66:69]
	s_barrier
	ds_read_b128 v[196:199], v194 offset:49152
	ds_read_b128 v[200:203], v194 offset:50176
	ds_read_b128 v[218:221], v194 offset:51200
	ds_read_b128 v[222:225], v194 offset:52224
	ds_read_b128 v[226:229], v194 offset:53248
	ds_read_b128 v[230:233], v194 offset:54272
	ds_read_b128 v[234:237], v194 offset:55296
	ds_read_b128 v[238:241], v194 offset:56320
	s_add_i32 s28, s54, s2
	s_add_i32 m0, s28, 0xffffff80
	s_nop 0
	global_load_lds_dwordx4 v0, s[26:27] offset:128
	s_add_i32 m0, s28, 0x2000
	s_add_u32 s26, s26, 0x80080
	v_lshl_add_u64 v[166:167], v[188:189], 0, s[34:35]
	s_addc_u32 s27, s27, 0
	s_add_i32 s28, s55, s2
	global_load_lds_dwordx4 v[166:167], off
	s_mov_b32 m0, s28
	s_nop 0
	global_load_lds_dwordx4 v0, s[26:27]
	s_add_i32 m0, s28, 0x2000
	s_nop 0
	global_load_lds_dwordx4 v154, s[26:27]
	v_lshl_add_u64 v[166:167], v[242:243], 0, s[34:35]
	s_mov_b32 m0, s53
	s_nop 0
	global_load_lds_dwordx4 v[166:167], off
	v_lshl_add_u64 v[166:167], v[244:245], 0, s[34:35]
	s_mov_b32 m0, s73
	s_nop 0
	global_load_lds_dwordx4 v[166:167], off
	s_waitcnt vmcnt(8)
	s_waitcnt lgkmcnt(0)
	s_barrier
	v_mfma_f32_16x16x32_bf16 v[62:65], v[114:117], v[196:199], v[62:65]
	v_mfma_f32_16x16x32_bf16 v[58:61], v[122:125], v[196:199], v[58:61]
	v_mfma_f32_16x16x32_bf16 v[46:49], v[114:117], v[218:221], v[46:49]
	v_mfma_f32_16x16x32_bf16 v[42:45], v[122:125], v[218:221], v[42:45]
	v_mfma_f32_16x16x32_bf16 v[30:33], v[114:117], v[226:229], v[30:33]
	v_mfma_f32_16x16x32_bf16 v[26:29], v[122:125], v[226:229], v[26:29]
	v_mfma_f32_16x16x32_bf16 v[14:17], v[114:117], v[234:237], v[14:17]
	v_mfma_f32_16x16x32_bf16 v[10:13], v[122:125], v[234:237], v[10:13]
	v_mfma_f32_16x16x32_bf16 v[62:65], v[118:121], v[200:203], v[62:65]
	v_mfma_f32_16x16x32_bf16 v[58:61], v[134:137], v[200:203], v[58:61]
	v_mfma_f32_16x16x32_bf16 v[46:49], v[118:121], v[222:225], v[46:49]
	v_mfma_f32_16x16x32_bf16 v[42:45], v[134:137], v[222:225], v[42:45]
	v_mfma_f32_16x16x32_bf16 v[30:33], v[118:121], v[230:233], v[30:33]
	v_mfma_f32_16x16x32_bf16 v[26:29], v[134:137], v[230:233], v[26:29]
	v_mfma_f32_16x16x32_bf16 v[14:17], v[118:121], v[238:241], v[14:17]
	v_mfma_f32_16x16x32_bf16 v[10:13], v[134:137], v[238:241], v[10:13]
	v_mfma_f32_16x16x32_bf16 v[54:57], v[146:149], v[196:199], v[54:57]
	v_mfma_f32_16x16x32_bf16 v[50:53], v[180:183], v[196:199], v[50:53]
	v_mfma_f32_16x16x32_bf16 v[38:41], v[146:149], v[218:221], v[38:41]
	v_mfma_f32_16x16x32_bf16 v[34:37], v[180:183], v[218:221], v[34:37]
	v_mfma_f32_16x16x32_bf16 v[22:25], v[146:149], v[226:229], v[22:25]
	v_mfma_f32_16x16x32_bf16 v[18:21], v[180:183], v[226:229], v[18:21]
	v_mfma_f32_16x16x32_bf16 v[6:9], v[146:149], v[234:237], v[6:9]
	v_mfma_f32_16x16x32_bf16 v[2:5], v[180:183], v[234:237], v[2:5]
	v_mfma_f32_16x16x32_bf16 v[54:57], v[150:153], v[200:203], v[54:57]
	v_mfma_f32_16x16x32_bf16 v[50:53], v[184:187], v[200:203], v[50:53]
	s_add_i32 vcc_hi, vcc_hi, 2
	v_mfma_f32_16x16x32_bf16 v[38:41], v[150:153], v[222:225], v[38:41]
	s_add_u32 s16, s16, 0x100
	v_mfma_f32_16x16x32_bf16 v[34:37], v[184:187], v[222:225], v[34:37]
	s_addc_u32 s17, s17, 0
	v_mfma_f32_16x16x32_bf16 v[22:25], v[150:153], v[230:233], v[22:25]
	s_add_u32 s78, s78, 0x100
	v_mfma_f32_16x16x32_bf16 v[18:21], v[184:187], v[230:233], v[18:21]
	s_addc_u32 vcc_lo, vcc_lo, 0
	v_mfma_f32_16x16x32_bf16 v[6:9], v[150:153], v[238:241], v[6:9]
	v_mfma_f32_16x16x32_bf16 v[2:5], v[184:187], v[238:241], v[2:5]
	s_barrier
	s_cmp_gt_u32 vcc_hi, 29
	s_cbranch_scc0 .LBB0_553
	s_and_b64 vcc, exec, s[6:7]
	s_cbranch_vccz .LBB0_556
	s_barrier

; #define PG8_STAGE(bufoff, gbase, voff) do { _Pragma("unroll") for (int _i = 0; _i < 2; ++_i) \
;         __builtin_amdgcn_global_load_lds((const unsigned*)((const char*)(gbase) + (voff)[_i]), (PG8_LAS unsigned*)(lds + (bufoff) + ldsw + _i * 8192), 16, 0, 0); } while (0)
; #define PG8_LDA(dst, b, h) do { _Pragma("unroll") for (int m = 0; m < 4; ++m) _Pragma("unroll") for (int k = 0; k < 2; ++k) dst[m][k] = *(const PG8_LAS bf16x8*)(lds + PG8_SA(b, h) + aoff + m * 2048 + k * 1024); } while (0)
; #define PG8_LDB(dst, b, h) do { _Pragma("unroll") for (int n = 0; n < 2; ++n) _Pragma("unroll") for (int k = 0; k < 2; ++k) dst[n][k] = *(const PG8_LAS bf16x8*)(lds + PG8_SB(b, h) + boff + n * 2048 + k * 1024); } while (0)
; #define PG8_MMA(ai, bj, At, Bt) do { __builtin_amdgcn_s_setprio(1); _Pragma("unroll") for (int m = 0; m < 4; ++m) _Pragma("unroll") for (int n = 0; n < 2; ++n) _Pragma("unroll") for (int k = 0; k < 2; ++k) \
;         acc[ai][bj][m][n] = __builtin_amdgcn_mfma_f32_16x16x32_bf16(Bt[n][k], At[m][k], acc[ai][bj][m][n], 0, 0, 0); __builtin_amdgcn_s_setprio(0); } while (0)
; #define PG8_WAIT_V(n) asm volatile("s_waitcnt vmcnt(" #n ")" ::: "memory")
; #define PG8_BAR __builtin_amdgcn_s_barrier()
; template <class Epi, class Sched, bool ALIGN_EPI = false, bool SP2 = false>
; __device__ __forceinline__ void gemm_phase(PG8_LAS unsigned char* lds, const Gemm g, const Sched& S, const Epi& E) {
;     ...
;         for (int t = 0; t < nt; t += 2) {
;             const bool last = (t == nt - 2);
;             const char* a1 = cA + (size_t)(t + 1) * kstep;
;             const char* a2 = last ? nA : cA + (size_t)(t + 2) * kstep; const char* b2 = last ? nB : cB + (size_t)(t + 2) * kstep;
;             const char* a3 = a2 + kstep; const char* b3 = b2 + kstep;
;             if (last && has_next) S.a_ready(nxt);
;             if constexpr (SP2) {
;             PG8_LDB(B0, 0, 0); PG8_LDB(B1, 0, 1); PG8_SCHED; PG8_LDA(At, 0, 0); PG8_STAGE(PG8_SA(1, 1), a1 + hstep, voffA);
;             PG8_WAIT_V(8); PG8_WAIT_L(0); PG8_BAR; PG8_MMA(0, 0, At, B0); PG8_MMA(0, 1, At, B1); PG8_BAR; PG8_SCHED;
;             PG8_LDA(At, 0, 1); PG8_STAGE(PG8_SB(0, 0), b2, voffB); PG8_STAGE(PG8_SB(0, 1), b2 + hstep, voffB); PG8_STAGE(PG8_SA(0, 0), a2, voffA);
;             PG8_WAIT_V(8); PG8_WAIT_L(0); PG8_BAR; PG8_MMA(1, 0, At, B0); PG8_MMA(1, 1, At, B1); PG8_BAR; PG8_SCHED;
.LBB0_659:
	ds_read_b128 v[142:145], v159
	ds_read_b128 v[146:149], v159 offset:1024
	ds_read_b128 v[150:153], v159 offset:2048
	ds_read_b128 v[154:157], v159 offset:3072
	ds_read_b128 v[164:167], v159 offset:16384
	ds_read_b128 v[180:183], v159 offset:17408
	ds_read_b128 v[184:187], v159 offset:18432
	ds_read_b128 v[188:191], v159 offset:19456
	s_add_i32 m0, s45, 0xc000
	ds_read_b128 v[192:195], v162
	ds_read_b128 v[196:199], v162 offset:1024
	ds_read_b128 v[200:203], v162 offset:2048
	ds_read_b128 v[218:221], v162 offset:3072
	ds_read_b128 v[222:225], v162 offset:4096
	ds_read_b128 v[226:229], v162 offset:5120
	ds_read_b128 v[230:233], v162 offset:6144
	ds_read_b128 v[234:237], v162 offset:7168
	global_load_lds_dwordx4 v138, s[16:17]
	s_add_i32 m0, s45, 0xe000
	s_nop 0
	global_load_lds_dwordx4 v140, s[16:17]
	s_add_u32 s26, s16, 0xfff80080
	s_addc_u32 s27, s17, -1
	s_add_i32 s54, 0, 0x10000
	s_cmp_eq_u32 s77, 28
	s_cselect_b32 s29, s23, s27
	s_cselect_b32 s28, s43, s26
	s_cselect_b32 s27, s21, s73
	s_cselect_b32 s26, s52, s53
	s_add_i32 s78, 0, 0x14000
	s_waitcnt vmcnt(8)
	s_waitcnt lgkmcnt(0)
	s_barrier
	v_mfma_f32_16x16x32_bf16 v[126:129], v[142:145], v[192:195], v[126:129]
	v_mfma_f32_16x16x32_bf16 v[118:121], v[150:153], v[192:195], v[118:121]
	v_mfma_f32_16x16x32_bf16 v[110:113], v[142:145], v[200:203], v[110:113]
	v_mfma_f32_16x16x32_bf16 v[102:105], v[150:153], v[200:203], v[102:105]
	v_mfma_f32_16x16x32_bf16 v[94:97], v[142:145], v[222:225], v[94:97]
	v_mfma_f32_16x16x32_bf16 v[86:89], v[150:153], v[222:225], v[86:89]
	v_mfma_f32_16x16x32_bf16 v[78:81], v[142:145], v[230:233], v[78:81]
	v_mfma_f32_16x16x32_bf16 v[70:73], v[150:153], v[230:233], v[70:73]
	v_mfma_f32_16x16x32_bf16 v[126:129], v[146:149], v[196:199], v[126:129]
	v_mfma_f32_16x16x32_bf16 v[118:121], v[154:157], v[196:199], v[118:121]
	v_mfma_f32_16x16x32_bf16 v[110:113], v[146:149], v[218:221], v[110:113]
	v_mfma_f32_16x16x32_bf16 v[102:105], v[154:157], v[218:221], v[102:105]
	v_mfma_f32_16x16x32_bf16 v[94:97], v[146:149], v[226:229], v[94:97]
	v_mfma_f32_16x16x32_bf16 v[86:89], v[154:157], v[226:229], v[86:89]
	v_mfma_f32_16x16x32_bf16 v[78:81], v[146:149], v[234:237], v[78:81]
	v_mfma_f32_16x16x32_bf16 v[70:73], v[154:157], v[234:237], v[70:73]
	v_mfma_f32_16x16x32_bf16 v[122:125], v[164:167], v[192:195], v[122:125]
	v_mfma_f32_16x16x32_bf16 v[114:117], v[184:187], v[192:195], v[114:117]
	v_mfma_f32_16x16x32_bf16 v[106:109], v[164:167], v[200:203], v[106:109]
	v_mfma_f32_16x16x32_bf16 v[98:101], v[184:187], v[200:203], v[98:101]
	v_mfma_f32_16x16x32_bf16 v[90:93], v[164:167], v[222:225], v[90:93]
	v_mfma_f32_16x16x32_bf16 v[82:85], v[184:187], v[222:225], v[82:85]
	v_mfma_f32_16x16x32_bf16 v[74:77], v[164:167], v[230:233], v[74:77]
	v_mfma_f32_16x16x32_bf16 v[66:69], v[184:187], v[230:233], v[66:69]
	v_mfma_f32_16x16x32_bf16 v[122:125], v[180:183], v[196:199], v[122:125]
	v_mfma_f32_16x16x32_bf16 v[114:117], v[188:191], v[196:199], v[114:117]
	v_mfma_f32_16x16x32_bf16 v[106:109], v[180:183], v[218:221], v[106:109]
	v_mfma_f32_16x16x32_bf16 v[98:101], v[188:191], v[218:221], v[98:101]
	v_mfma_f32_16x16x32_bf16 v[90:93], v[180:183], v[226:229], v[90:93]
	v_mfma_f32_16x16x32_bf16 v[82:85], v[188:191], v[226:229], v[82:85]
	v_mfma_f32_16x16x32_bf16 v[74:77], v[180:183], v[234:237], v[74:77]
	v_mfma_f32_16x16x32_bf16 v[66:69], v[188:191], v[234:237], v[66:69]
	s_barrier
	ds_read_b128 v[192:195], v162 offset:16384
	ds_read_b128 v[196:199], v162 offset:17408
	ds_read_b128 v[200:203], v162 offset:18432
	ds_read_b128 v[218:221], v162 offset:19456
	ds_read_b128 v[222:225], v162 offset:20480
	ds_read_b128 v[226:229], v162 offset:21504
	ds_read_b128 v[230:233], v162 offset:22528
	ds_read_b128 v[234:237], v162 offset:23552
	s_add_i32 s54, s54, s38
	s_mov_b32 m0, s54
	s_nop 0
	global_load_lds_dwordx4 v0, s[26:27]
	s_add_i32 m0, s54, 0x2000
	s_add_u32 s54, s26, 0x80000
	v_lshl_add_u64 v[240:241], s[26:27], 0, v[130:131]
	s_addc_u32 s55, s27, 0
	s_add_i32 s78, s78, s38
	global_load_lds_dwordx4 v130, s[26:27]
	s_mov_b32 m0, s78
	v_lshl_add_u64 v[244:245], s[28:29], 0, v[132:133]
	global_load_lds_dwordx4 v0, s[54:55]
	s_add_i32 m0, s78, 0x2000
	s_nop 0
	global_load_lds_dwordx4 v130, s[54:55]
	v_lshl_add_u64 v[242:243], s[28:29], 0, v[134:135]
	s_mov_b32 m0, s45
	s_nop 0
	global_load_lds_dwordx4 v134, s[28:29]
	s_mov_b32 m0, s46
	s_nop 0
	global_load_lds_dwordx4 v132, s[28:29]
	s_waitcnt vmcnt(8)
	s_waitcnt lgkmcnt(0)
	s_barrier
	v_mfma_f32_16x16x32_bf16 v[62:65], v[142:145], v[192:195], v[62:65]
	v_mfma_f32_16x16x32_bf16 v[54:57], v[150:153], v[192:195], v[54:57]
	v_mfma_f32_16x16x32_bf16 v[46:49], v[142:145], v[200:203], v[46:49]
	v_mfma_f32_16x16x32_bf16 v[38:41], v[150:153], v[200:203], v[38:41]
	v_mfma_f32_16x16x32_bf16 v[30:33], v[142:145], v[222:225], v[30:33]
	v_mfma_f32_16x16x32_bf16 v[22:25], v[150:153], v[222:225], v[22:25]
	v_mfma_f32_16x16x32_bf16 v[14:17], v[142:145], v[230:233], v[14:17]
	v_mfma_f32_16x16x32_bf16 v[6:9], v[150:153], v[230:233], v[6:9]
	v_mfma_f32_16x16x32_bf16 v[62:65], v[146:149], v[196:199], v[62:65]
	v_mfma_f32_16x16x32_bf16 v[54:57], v[154:157], v[196:199], v[54:57]
	v_mfma_f32_16x16x32_bf16 v[46:49], v[146:149], v[218:221], v[46:49]
	v_mfma_f32_16x16x32_bf16 v[38:41], v[154:157], v[218:221], v[38:41]
	v_mfma_f32_16x16x32_bf16 v[30:33], v[146:149], v[226:229], v[30:33]
	v_mfma_f32_16x16x32_bf16 v[22:25], v[154:157], v[226:229], v[22:25]
	v_mfma_f32_16x16x32_bf16 v[14:17], v[146:149], v[234:237], v[14:17]
	v_mfma_f32_16x16x32_bf16 v[6:9], v[154:157], v[234:237], v[6:9]
	v_mfma_f32_16x16x32_bf16 v[58:61], v[164:167], v[192:195], v[58:61]
	v_mfma_f32_16x16x32_bf16 v[50:53], v[184:187], v[192:195], v[50:53]
	v_mfma_f32_16x16x32_bf16 v[42:45], v[164:167], v[200:203], v[42:45]
	v_mfma_f32_16x16x32_bf16 v[34:37], v[184:187], v[200:203], v[34:37]
	v_mfma_f32_16x16x32_bf16 v[26:29], v[164:167], v[222:225], v[26:29]
	v_mfma_f32_16x16x32_bf16 v[18:21], v[184:187], v[222:225], v[18:21]
	v_mfma_f32_16x16x32_bf16 v[10:13], v[164:167], v[230:233], v[10:13]
	v_mfma_f32_16x16x32_bf16 v[2:5], v[184:187], v[230:233], v[2:5]
	v_mfma_f32_16x16x32_bf16 v[58:61], v[180:183], v[196:199], v[58:61]
	v_mfma_f32_16x16x32_bf16 v[50:53], v[188:191], v[196:199], v[50:53]
	v_mfma_f32_16x16x32_bf16 v[42:45], v[180:183], v[218:221], v[42:45]
	v_mfma_f32_16x16x32_bf16 v[34:37], v[188:191], v[218:221], v[34:37]
	v_mfma_f32_16x16x32_bf16 v[26:29], v[180:183], v[226:229], v[26:29]
	v_mfma_f32_16x16x32_bf16 v[18:21], v[188:191], v[226:229], v[18:21]
	v_mfma_f32_16x16x32_bf16 v[10:13], v[180:183], v[234:237], v[10:13]
	v_mfma_f32_16x16x32_bf16 v[2:5], v[188:191], v[234:237], v[2:5]
	s_barrier
; #define PG8_STAGE(bufoff, gbase, voff) do { _Pragma("unroll") for (int _i = 0; _i < 2; ++_i) \
;         __builtin_amdgcn_global_load_lds((const unsigned*)((const char*)(gbase) + (voff)[_i]), (PG8_LAS unsigned*)(lds + (bufoff) + ldsw + _i * 8192), 16, 0, 0); } while (0)
; #define PG8_LDA(dst, b, h) do { _Pragma("unroll") for (int m = 0; m < 4; ++m) _Pragma("unroll") for (int k = 0; k < 2; ++k) dst[m][k] = *(const PG8_LAS bf16x8*)(lds + PG8_SA(b, h) + aoff + m * 2048 + k * 1024); } while (0)
; #define PG8_LDB(dst, b, h) do { _Pragma("unroll") for (int n = 0; n < 2; ++n) _Pragma("unroll") for (int k = 0; k < 2; ++k) dst[n][k] = *(const PG8_LAS bf16x8*)(lds + PG8_SB(b, h) + boff + n * 2048 + k * 1024); } while (0)
; #define PG8_MMA(ai, bj, At, Bt) do { __builtin_amdgcn_s_setprio(1); _Pragma("unroll") for (int m = 0; m < 4; ++m) _Pragma("unroll") for (int n = 0; n < 2; ++n) _Pragma("unroll") for (int k = 0; k < 2; ++k) \
;         acc[ai][bj][m][n] = __builtin_amdgcn_mfma_f32_16x16x32_bf16(Bt[n][k], At[m][k], acc[ai][bj][m][n], 0, 0, 0); __builtin_amdgcn_s_setprio(0); } while (0)
; #define PG8_WAIT_V(n) asm volatile("s_waitcnt vmcnt(" #n ")" ::: "memory")
; #define PG8_WAIT_L(n) asm volatile("s_waitcnt lgkmcnt(" #n ")" ::: "memory")
; #define PG8_BAR __builtin_amdgcn_s_barrier()
; #define PG8_SCHED __builtin_amdgcn_sched_barrier(0)
; template <class Epi, class Sched, bool ALIGN_EPI = false, bool SP2 = false>
; __device__ __forceinline__ void gemm_phase(PG8_LAS unsigned char* lds, const Gemm g, const Sched& S, const Epi& E) {
;     ...
;             PG8_LDB(B0, 1, 0); PG8_LDB(B1, 1, 1); PG8_SCHED; PG8_LDA(At, 1, 0); PG8_STAGE(PG8_SA(0, 1), a2 + hstep, voffA);
;             PG8_WAIT_V(8); PG8_WAIT_L(0); PG8_BAR; PG8_MMA(0, 0, At, B0); PG8_MMA(0, 1, At, B1); PG8_BAR; PG8_SCHED;
;             PG8_LDA(At, 1, 1); PG8_STAGE(PG8_SB(1, 0), b3, voffB); PG8_STAGE(PG8_SB(1, 1), b3 + hstep, voffB); PG8_STAGE(PG8_SA(1, 0), a3, voffA);
;             PG8_WAIT_V(8); PG8_WAIT_L(0); PG8_BAR; PG8_MMA(1, 0, At, B0); PG8_MMA(1, 1, At, B1); PG8_BAR; PG8_SCHED;
	ds_read_b128 v[142:145], v159 offset:32768
	ds_read_b128 v[146:149], v159 offset:33792
	ds_read_b128 v[150:153], v159 offset:34816
	ds_read_b128 v[154:157], v159 offset:35840
	ds_read_b128 v[164:167], v159 offset:49152
	ds_read_b128 v[180:183], v159 offset:50176
	ds_read_b128 v[184:187], v159 offset:51200
	ds_read_b128 v[188:191], v159 offset:52224
	s_add_i32 s54, 0, 0x18000
	s_add_i32 s55, 0, 0x1c000
	s_add_u32 s28, s28, 0x80000
	s_addc_u32 s29, s29, 0
	s_mov_b32 m0, s47
	ds_read_b128 v[192:195], v162 offset:32768
	ds_read_b128 v[196:199], v162 offset:33792
	ds_read_b128 v[200:203], v162 offset:34816
	ds_read_b128 v[218:221], v162 offset:35840
	ds_read_b128 v[222:225], v162 offset:36864
	ds_read_b128 v[226:229], v162 offset:37888
	ds_read_b128 v[230:233], v162 offset:38912
	ds_read_b128 v[234:237], v162 offset:39936
	global_load_lds_dwordx4 v134, s[28:29]
	s_mov_b32 m0, s48
	s_nop 0
	global_load_lds_dwordx4 v132, s[28:29]
	s_waitcnt vmcnt(8)
	s_waitcnt lgkmcnt(0)
	s_barrier
	v_mfma_f32_16x16x32_bf16 v[126:129], v[142:145], v[192:195], v[126:129]
	v_mfma_f32_16x16x32_bf16 v[118:121], v[150:153], v[192:195], v[118:121]
	v_mfma_f32_16x16x32_bf16 v[110:113], v[142:145], v[200:203], v[110:113]
	v_mfma_f32_16x16x32_bf16 v[102:105], v[150:153], v[200:203], v[102:105]
	v_mfma_f32_16x16x32_bf16 v[94:97], v[142:145], v[222:225], v[94:97]
	v_mfma_f32_16x16x32_bf16 v[86:89], v[150:153], v[222:225], v[86:89]
	v_mfma_f32_16x16x32_bf16 v[78:81], v[142:145], v[230:233], v[78:81]
	v_mfma_f32_16x16x32_bf16 v[70:73], v[150:153], v[230:233], v[70:73]
	v_mfma_f32_16x16x32_bf16 v[126:129], v[146:149], v[196:199], v[126:129]
	v_mfma_f32_16x16x32_bf16 v[118:121], v[154:157], v[196:199], v[118:121]
	v_mfma_f32_16x16x32_bf16 v[110:113], v[146:149], v[218:221], v[110:113]
	v_mfma_f32_16x16x32_bf16 v[102:105], v[154:157], v[218:221], v[102:105]
	v_mfma_f32_16x16x32_bf16 v[94:97], v[146:149], v[226:229], v[94:97]
	v_mfma_f32_16x16x32_bf16 v[86:89], v[154:157], v[226:229], v[86:89]
	v_mfma_f32_16x16x32_bf16 v[78:81], v[146:149], v[234:237], v[78:81]
	v_mfma_f32_16x16x32_bf16 v[70:73], v[154:157], v[234:237], v[70:73]
	v_mfma_f32_16x16x32_bf16 v[122:125], v[164:167], v[192:195], v[122:125]
	v_mfma_f32_16x16x32_bf16 v[114:117], v[184:187], v[192:195], v[114:117]
	v_mfma_f32_16x16x32_bf16 v[106:109], v[164:167], v[200:203], v[106:109]
	v_mfma_f32_16x16x32_bf16 v[98:101], v[184:187], v[200:203], v[98:101]
	v_mfma_f32_16x16x32_bf16 v[90:93], v[164:167], v[222:225], v[90:93]
	v_mfma_f32_16x16x32_bf16 v[82:85], v[184:187], v[222:225], v[82:85]
	v_mfma_f32_16x16x32_bf16 v[74:77], v[164:167], v[230:233], v[74:77]
	v_mfma_f32_16x16x32_bf16 v[66:69], v[184:187], v[230:233], v[66:69]
	v_mfma_f32_16x16x32_bf16 v[122:125], v[180:183], v[196:199], v[122:125]
	v_mfma_f32_16x16x32_bf16 v[114:117], v[188:191], v[196:199], v[114:117]
	v_mfma_f32_16x16x32_bf16 v[106:109], v[180:183], v[218:221], v[106:109]
	v_mfma_f32_16x16x32_bf16 v[98:101], v[188:191], v[218:221], v[98:101]
	v_mfma_f32_16x16x32_bf16 v[90:93], v[180:183], v[226:229], v[90:93]
	v_mfma_f32_16x16x32_bf16 v[82:85], v[188:191], v[226:229], v[82:85]
	v_mfma_f32_16x16x32_bf16 v[74:77], v[180:183], v[234:237], v[74:77]
	v_mfma_f32_16x16x32_bf16 v[66:69], v[188:191], v[234:237], v[66:69]
	s_barrier
	ds_read_b128 v[192:195], v162 offset:49152
	ds_read_b128 v[196:199], v162 offset:50176
	ds_read_b128 v[200:203], v162 offset:51200
	ds_read_b128 v[218:221], v162 offset:52224
	ds_read_b128 v[222:225], v162 offset:53248
	ds_read_b128 v[226:229], v162 offset:54272
	ds_read_b128 v[230:233], v162 offset:55296
	ds_read_b128 v[234:237], v162 offset:56320
	s_add_i32 s28, s54, s38
	s_add_i32 m0, s28, 0xffffff80
	s_nop 0
	global_load_lds_dwordx4 v0, s[26:27] offset:128
	s_add_i32 m0, s28, 0x2000
	s_add_u32 s26, s26, 0x80080
	v_lshl_add_u64 v[238:239], v[240:241], 0, s[34:35]
	s_addc_u32 s27, s27, 0
	s_add_i32 s28, s55, s38
	global_load_lds_dwordx4 v[238:239], off
	s_mov_b32 m0, s28
	s_nop 0
	global_load_lds_dwordx4 v0, s[26:27]
	s_add_i32 m0, s28, 0x2000
	s_nop 0
	global_load_lds_dwordx4 v130, s[26:27]
	v_lshl_add_u64 v[238:239], v[242:243], 0, s[34:35]
	s_mov_b32 m0, s4
	s_nop 0
	global_load_lds_dwordx4 v[238:239], off
	v_lshl_add_u64 v[238:239], v[244:245], 0, s[34:35]
	s_mov_b32 m0, s49
	s_nop 0
	global_load_lds_dwordx4 v[238:239], off
	s_waitcnt vmcnt(8)
	s_waitcnt lgkmcnt(0)
	s_barrier
	v_mfma_f32_16x16x32_bf16 v[62:65], v[142:145], v[192:195], v[62:65]
	v_mfma_f32_16x16x32_bf16 v[54:57], v[150:153], v[192:195], v[54:57]
	v_mfma_f32_16x16x32_bf16 v[46:49], v[142:145], v[200:203], v[46:49]
	v_mfma_f32_16x16x32_bf16 v[38:41], v[150:153], v[200:203], v[38:41]
	v_mfma_f32_16x16x32_bf16 v[30:33], v[142:145], v[222:225], v[30:33]
	v_mfma_f32_16x16x32_bf16 v[22:25], v[150:153], v[222:225], v[22:25]
	v_mfma_f32_16x16x32_bf16 v[14:17], v[142:145], v[230:233], v[14:17]
	v_mfma_f32_16x16x32_bf16 v[6:9], v[150:153], v[230:233], v[6:9]
	v_mfma_f32_16x16x32_bf16 v[62:65], v[146:149], v[196:199], v[62:65]
	v_mfma_f32_16x16x32_bf16 v[54:57], v[154:157], v[196:199], v[54:57]
	v_mfma_f32_16x16x32_bf16 v[46:49], v[146:149], v[218:221], v[46:49]
	v_mfma_f32_16x16x32_bf16 v[38:41], v[154:157], v[218:221], v[38:41]
	v_mfma_f32_16x16x32_bf16 v[30:33], v[146:149], v[226:229], v[30:33]
	v_mfma_f32_16x16x32_bf16 v[22:25], v[154:157], v[226:229], v[22:25]
	v_mfma_f32_16x16x32_bf16 v[14:17], v[146:149], v[234:237], v[14:17]
	v_mfma_f32_16x16x32_bf16 v[6:9], v[154:157], v[234:237], v[6:9]
	v_mfma_f32_16x16x32_bf16 v[58:61], v[164:167], v[192:195], v[58:61]
	v_mfma_f32_16x16x32_bf16 v[50:53], v[184:187], v[192:195], v[50:53]
	v_mfma_f32_16x16x32_bf16 v[42:45], v[164:167], v[200:203], v[42:45]
	v_mfma_f32_16x16x32_bf16 v[34:37], v[184:187], v[200:203], v[34:37]
	v_mfma_f32_16x16x32_bf16 v[26:29], v[164:167], v[222:225], v[26:29]
	v_mfma_f32_16x16x32_bf16 v[18:21], v[184:187], v[222:225], v[18:21]
	v_mfma_f32_16x16x32_bf16 v[10:13], v[164:167], v[230:233], v[10:13]
	v_mfma_f32_16x16x32_bf16 v[2:5], v[184:187], v[230:233], v[2:5]
	v_mfma_f32_16x16x32_bf16 v[58:61], v[180:183], v[196:199], v[58:61]
	v_mfma_f32_16x16x32_bf16 v[50:53], v[188:191], v[196:199], v[50:53]
	s_add_i32 s77, s77, 2
	v_mfma_f32_16x16x32_bf16 v[42:45], v[180:183], v[218:221], v[42:45]
	s_add_u32 s16, s16, 0x100
	v_mfma_f32_16x16x32_bf16 v[34:37], v[188:191], v[218:221], v[34:37]
	s_addc_u32 s17, s17, 0
	v_mfma_f32_16x16x32_bf16 v[26:29], v[180:183], v[226:229], v[26:29]
	s_add_u32 s53, s53, 0x100
	v_mfma_f32_16x16x32_bf16 v[18:21], v[188:191], v[226:229], v[18:21]
	s_addc_u32 s73, s73, 0
	v_mfma_f32_16x16x32_bf16 v[10:13], v[180:183], v[234:237], v[10:13]
	v_mfma_f32_16x16x32_bf16 v[2:5], v[188:191], v[234:237], v[2:5]
	s_barrier
	s_cmp_gt_u32 s77, 29
	s_cbranch_scc0 .LBB0_659
	s_and_b64 vcc, exec, s[18:19]
	s_cbranch_vccz .LBB0_662
	s_barrier

; #define PG8_STAGE(bufoff, gbase, voff) do { _Pragma("unroll") for (int _i = 0; _i < 2; ++_i) \
;         __builtin_amdgcn_global_load_lds((const unsigned*)((const char*)(gbase) + (voff)[_i]), (PG8_LAS unsigned*)(lds + (bufoff) + ldsw + _i * 8192), 16, 0, 0); } while (0)
; #define PG8_LDA(dst, b, h) do { _Pragma("unroll") for (int m = 0; m < 4; ++m) _Pragma("unroll") for (int k = 0; k < 2; ++k) dst[m][k] = *(const PG8_LAS bf16x8*)(lds + PG8_SA(b, h) + aoff + m * 2048 + k * 1024); } while (0)
; #define PG8_LDB(dst, b, h) do { _Pragma("unroll") for (int n = 0; n < 2; ++n) _Pragma("unroll") for (int k = 0; k < 2; ++k) dst[n][k] = *(const PG8_LAS bf16x8*)(lds + PG8_SB(b, h) + boff + n * 2048 + k * 1024); } while (0)
; #define PG8_MMA(ai, bj, At, Bt) do { __builtin_amdgcn_s_setprio(1); _Pragma("unroll") for (int m = 0; m < 4; ++m) _Pragma("unroll") for (int n = 0; n < 2; ++n) _Pragma("unroll") for (int k = 0; k < 2; ++k) \
;         acc[ai][bj][m][n] = __builtin_amdgcn_mfma_f32_16x16x32_bf16(Bt[n][k], At[m][k], acc[ai][bj][m][n], 0, 0, 0); __builtin_amdgcn_s_setprio(0); } while (0)
; #define PG8_WAIT_V(n) asm volatile("s_waitcnt vmcnt(" #n ")" ::: "memory")
; #define PG8_BAR __builtin_amdgcn_s_barrier()
; template <class Epi, class Sched, bool ALIGN_EPI = false, bool SP2 = false>
; __device__ __forceinline__ void gemm_phase(PG8_LAS unsigned char* lds, const Gemm g, const Sched& S, const Epi& E) {
;     ...
;         for (int t = 0; t < nt; t += 2) {
;             const bool last = (t == nt - 2);
;             const char* a1 = cA + (size_t)(t + 1) * kstep;
;             const char* a2 = last ? nA : cA + (size_t)(t + 2) * kstep; const char* b2 = last ? nB : cB + (size_t)(t + 2) * kstep;
;             const char* a3 = a2 + kstep; const char* b3 = b2 + kstep;
;             if (last && has_next) S.a_ready(nxt);
;             if constexpr (SP2) {
;             PG8_LDB(B0, 0, 0); PG8_LDB(B1, 0, 1); PG8_SCHED; PG8_LDA(At, 0, 0); PG8_STAGE(PG8_SA(1, 1), a1 + hstep, voffA);
;             PG8_WAIT_V(8); PG8_WAIT_L(0); PG8_BAR; PG8_MMA(0, 0, At, B0); PG8_MMA(0, 1, At, B1); PG8_BAR; PG8_SCHED;
;             PG8_LDA(At, 0, 1); PG8_STAGE(PG8_SB(0, 0), b2, voffB); PG8_STAGE(PG8_SB(0, 1), b2 + hstep, voffB); PG8_STAGE(PG8_SA(0, 0), a2, voffA);
;             PG8_WAIT_V(8); PG8_WAIT_L(0); PG8_BAR; PG8_MMA(1, 0, At, B0); PG8_MMA(1, 1, At, B1); PG8_BAR; PG8_SCHED;
.LBB0_802:
	ds_read_b128 v[122:125], v199
	ds_read_b128 v[134:137], v199 offset:1024
	ds_read_b128 v[138:141], v199 offset:2048
	ds_read_b128 v[142:145], v199 offset:3072
	ds_read_b128 v[146:149], v199 offset:16384
	ds_read_b128 v[150:153], v199 offset:17408
	ds_read_b128 v[154:157], v199 offset:18432
	ds_read_b128 v[182:185], v199 offset:19456
	s_add_i32 m0, s46, 0xc000
	ds_read_b128 v[186:189], v202
	ds_read_b128 v[190:193], v202 offset:1024
	ds_read_b128 v[194:197], v202 offset:2048
	ds_read_b128 v[218:221], v202 offset:3072
	ds_read_b128 v[222:225], v202 offset:4096
	ds_read_b128 v[226:229], v202 offset:5120
	ds_read_b128 v[230:233], v202 offset:6144
	ds_read_b128 v[234:237], v202 offset:7168
	global_load_lds_dwordx4 v166, s[22:23]
	s_add_i32 m0, s46, 0xe000
	s_nop 0
	global_load_lds_dwordx4 v180, s[22:23]
	s_add_u32 s24, s22, 0x100
	s_addc_u32 s25, s23, 0
	s_add_i32 s54, 0, 0x10000
	s_cmpk_eq_i32 s78, 0x54
	s_cselect_b32 s29, s19, s25
	s_cselect_b32 s28, s18, s24
	s_cselect_b32 s27, s21, s45
	s_cselect_b32 s26, s20, s44
	s_add_i32 s55, 0, 0x14000
	s_waitcnt vmcnt(8)
	s_waitcnt lgkmcnt(0)
	s_barrier
	v_mfma_f32_16x16x32_bf16 v[130:133], v[122:125], v[186:189], v[130:133]
	v_mfma_f32_16x16x32_bf16 v[126:129], v[138:141], v[186:189], v[126:129]
	v_mfma_f32_16x16x32_bf16 v[110:113], v[122:125], v[194:197], v[110:113]
	v_mfma_f32_16x16x32_bf16 v[106:109], v[138:141], v[194:197], v[106:109]
	v_mfma_f32_16x16x32_bf16 v[94:97], v[122:125], v[222:225], v[94:97]
	v_mfma_f32_16x16x32_bf16 v[90:93], v[138:141], v[222:225], v[90:93]
	v_mfma_f32_16x16x32_bf16 v[78:81], v[122:125], v[230:233], v[78:81]
	v_mfma_f32_16x16x32_bf16 v[74:77], v[138:141], v[230:233], v[74:77]
	v_mfma_f32_16x16x32_bf16 v[130:133], v[134:137], v[190:193], v[130:133]
	v_mfma_f32_16x16x32_bf16 v[126:129], v[142:145], v[190:193], v[126:129]
	v_mfma_f32_16x16x32_bf16 v[110:113], v[134:137], v[218:221], v[110:113]
	v_mfma_f32_16x16x32_bf16 v[106:109], v[142:145], v[218:221], v[106:109]
	v_mfma_f32_16x16x32_bf16 v[94:97], v[134:137], v[226:229], v[94:97]
	v_mfma_f32_16x16x32_bf16 v[90:93], v[142:145], v[226:229], v[90:93]
	v_mfma_f32_16x16x32_bf16 v[78:81], v[134:137], v[234:237], v[78:81]
	v_mfma_f32_16x16x32_bf16 v[74:77], v[142:145], v[234:237], v[74:77]
	v_mfma_f32_16x16x32_bf16 v[118:121], v[146:149], v[186:189], v[118:121]
	v_mfma_f32_16x16x32_bf16 v[114:117], v[154:157], v[186:189], v[114:117]
	v_mfma_f32_16x16x32_bf16 v[102:105], v[146:149], v[194:197], v[102:105]
	v_mfma_f32_16x16x32_bf16 v[98:101], v[154:157], v[194:197], v[98:101]
	v_mfma_f32_16x16x32_bf16 v[86:89], v[146:149], v[222:225], v[86:89]
	v_mfma_f32_16x16x32_bf16 v[82:85], v[154:157], v[222:225], v[82:85]
	v_mfma_f32_16x16x32_bf16 v[70:73], v[146:149], v[230:233], v[70:73]
	v_mfma_f32_16x16x32_bf16 v[66:69], v[154:157], v[230:233], v[66:69]
	v_mfma_f32_16x16x32_bf16 v[118:121], v[150:153], v[190:193], v[118:121]
	v_mfma_f32_16x16x32_bf16 v[114:117], v[182:185], v[190:193], v[114:117]
	v_mfma_f32_16x16x32_bf16 v[102:105], v[150:153], v[218:221], v[102:105]
	v_mfma_f32_16x16x32_bf16 v[98:101], v[182:185], v[218:221], v[98:101]
	v_mfma_f32_16x16x32_bf16 v[86:89], v[150:153], v[226:229], v[86:89]
	v_mfma_f32_16x16x32_bf16 v[82:85], v[182:185], v[226:229], v[82:85]
	v_mfma_f32_16x16x32_bf16 v[70:73], v[150:153], v[234:237], v[70:73]
	v_mfma_f32_16x16x32_bf16 v[66:69], v[182:185], v[234:237], v[66:69]
	s_barrier
	ds_read_b128 v[186:189], v202 offset:16384
	ds_read_b128 v[190:193], v202 offset:17408
	ds_read_b128 v[194:197], v202 offset:18432
	ds_read_b128 v[218:221], v202 offset:19456
	ds_read_b128 v[222:225], v202 offset:20480
	ds_read_b128 v[226:229], v202 offset:21504
	ds_read_b128 v[230:233], v202 offset:22528
	ds_read_b128 v[234:237], v202 offset:23552
	s_add_i32 s22, s54, s2
	s_mov_b32 m0, s22
	s_nop 0
	global_load_lds_dwordx4 v0, s[26:27]
	s_add_i32 m0, s22, 0x2000
	s_add_u32 s22, s26, 0x160000
	v_lshl_add_u64 v[240:241], s[26:27], 0, v[158:159]
	s_addc_u32 s23, s27, 0
	s_add_i32 s54, s55, s2
	global_load_lds_dwordx4 v158, s[26:27]
	s_mov_b32 m0, s54
	s_nop 0
	global_load_lds_dwordx4 v0, s[22:23]
	s_add_i32 m0, s54, 0x2000
	s_nop 0
	global_load_lds_dwordx4 v158, s[22:23]
	s_mov_b32 m0, s46
	s_nop 0
	global_load_lds_dwordx4 v162, s[28:29]
	s_mov_b32 m0, s47
	s_nop 0
	global_load_lds_dwordx4 v160, s[28:29]
	s_waitcnt vmcnt(8)
	s_waitcnt lgkmcnt(0)
	s_barrier
	v_mfma_f32_16x16x32_bf16 v[62:65], v[122:125], v[186:189], v[62:65]
	v_mfma_f32_16x16x32_bf16 v[58:61], v[138:141], v[186:189], v[58:61]
	v_mfma_f32_16x16x32_bf16 v[46:49], v[122:125], v[194:197], v[46:49]
	v_mfma_f32_16x16x32_bf16 v[42:45], v[138:141], v[194:197], v[42:45]
	v_mfma_f32_16x16x32_bf16 v[30:33], v[122:125], v[222:225], v[30:33]
	v_mfma_f32_16x16x32_bf16 v[26:29], v[138:141], v[222:225], v[26:29]
	v_mfma_f32_16x16x32_bf16 v[14:17], v[122:125], v[230:233], v[14:17]
	v_mfma_f32_16x16x32_bf16 v[10:13], v[138:141], v[230:233], v[10:13]
	v_mfma_f32_16x16x32_bf16 v[62:65], v[134:137], v[190:193], v[62:65]
	v_mfma_f32_16x16x32_bf16 v[58:61], v[142:145], v[190:193], v[58:61]
	v_mfma_f32_16x16x32_bf16 v[46:49], v[134:137], v[218:221], v[46:49]
	v_mfma_f32_16x16x32_bf16 v[42:45], v[142:145], v[218:221], v[42:45]
	v_mfma_f32_16x16x32_bf16 v[30:33], v[134:137], v[226:229], v[30:33]
	v_mfma_f32_16x16x32_bf16 v[26:29], v[142:145], v[226:229], v[26:29]
	v_mfma_f32_16x16x32_bf16 v[14:17], v[134:137], v[234:237], v[14:17]
	v_mfma_f32_16x16x32_bf16 v[10:13], v[142:145], v[234:237], v[10:13]
	v_mfma_f32_16x16x32_bf16 v[54:57], v[146:149], v[186:189], v[54:57]
	v_mfma_f32_16x16x32_bf16 v[50:53], v[154:157], v[186:189], v[50:53]
	v_mfma_f32_16x16x32_bf16 v[38:41], v[146:149], v[194:197], v[38:41]
	v_mfma_f32_16x16x32_bf16 v[34:37], v[154:157], v[194:197], v[34:37]
	v_mfma_f32_16x16x32_bf16 v[22:25], v[146:149], v[222:225], v[22:25]
	v_mfma_f32_16x16x32_bf16 v[18:21], v[154:157], v[222:225], v[18:21]
	v_mfma_f32_16x16x32_bf16 v[6:9], v[146:149], v[230:233], v[6:9]
	v_mfma_f32_16x16x32_bf16 v[2:5], v[154:157], v[230:233], v[2:5]
	v_mfma_f32_16x16x32_bf16 v[54:57], v[150:153], v[190:193], v[54:57]
	v_mfma_f32_16x16x32_bf16 v[50:53], v[182:185], v[190:193], v[50:53]
	v_mfma_f32_16x16x32_bf16 v[38:41], v[150:153], v[218:221], v[38:41]
	v_mfma_f32_16x16x32_bf16 v[34:37], v[182:185], v[218:221], v[34:37]
	v_mfma_f32_16x16x32_bf16 v[22:25], v[150:153], v[226:229], v[22:25]
	v_mfma_f32_16x16x32_bf16 v[18:21], v[182:185], v[226:229], v[18:21]
	v_mfma_f32_16x16x32_bf16 v[6:9], v[150:153], v[234:237], v[6:9]
	v_mfma_f32_16x16x32_bf16 v[2:5], v[182:185], v[234:237], v[2:5]
	s_barrier
; #define PG8_STAGE(bufoff, gbase, voff) do { _Pragma("unroll") for (int _i = 0; _i < 2; ++_i) \
;         __builtin_amdgcn_global_load_lds((const unsigned*)((const char*)(gbase) + (voff)[_i]), (PG8_LAS unsigned*)(lds + (bufoff) + ldsw + _i * 8192), 16, 0, 0); } while (0)
; #define PG8_LDA(dst, b, h) do { _Pragma("unroll") for (int m = 0; m < 4; ++m) _Pragma("unroll") for (int k = 0; k < 2; ++k) dst[m][k] = *(const PG8_LAS bf16x8*)(lds + PG8_SA(b, h) + aoff + m * 2048 + k * 1024); } while (0)
; #define PG8_LDB(dst, b, h) do { _Pragma("unroll") for (int n = 0; n < 2; ++n) _Pragma("unroll") for (int k = 0; k < 2; ++k) dst[n][k] = *(const PG8_LAS bf16x8*)(lds + PG8_SB(b, h) + boff + n * 2048 + k * 1024); } while (0)
; #define PG8_MMA(ai, bj, At, Bt) do { __builtin_amdgcn_s_setprio(1); _Pragma("unroll") for (int m = 0; m < 4; ++m) _Pragma("unroll") for (int n = 0; n < 2; ++n) _Pragma("unroll") for (int k = 0; k < 2; ++k) \
;         acc[ai][bj][m][n] = __builtin_amdgcn_mfma_f32_16x16x32_bf16(Bt[n][k], At[m][k], acc[ai][bj][m][n], 0, 0, 0); __builtin_amdgcn_s_setprio(0); } while (0)
; #define PG8_WAIT_V(n) asm volatile("s_waitcnt vmcnt(" #n ")" ::: "memory")
; #define PG8_WAIT_L(n) asm volatile("s_waitcnt lgkmcnt(" #n ")" ::: "memory")
; #define PG8_BAR __builtin_amdgcn_s_barrier()
; #define PG8_SCHED __builtin_amdgcn_sched_barrier(0)
; template <class Epi, class Sched, bool ALIGN_EPI = false, bool SP2 = false>
; __device__ __forceinline__ void gemm_phase(PG8_LAS unsigned char* lds, const Gemm g, const Sched& S, const Epi& E) {
;     ...
;             PG8_LDB(B0, 1, 0); PG8_LDB(B1, 1, 1); PG8_SCHED; PG8_LDA(At, 1, 0); PG8_STAGE(PG8_SA(0, 1), a2 + hstep, voffA);
;             PG8_WAIT_V(8); PG8_WAIT_L(0); PG8_BAR; PG8_MMA(0, 0, At, B0); PG8_MMA(0, 1, At, B1); PG8_BAR; PG8_SCHED;
;             PG8_LDA(At, 1, 1); PG8_STAGE(PG8_SB(1, 0), b3, voffB); PG8_STAGE(PG8_SB(1, 1), b3 + hstep, voffB); PG8_STAGE(PG8_SA(1, 0), a3, voffA);
;             PG8_WAIT_V(8); PG8_WAIT_L(0); PG8_BAR; PG8_MMA(1, 0, At, B0); PG8_MMA(1, 1, At, B1); PG8_BAR; PG8_SCHED;
	ds_read_b128 v[122:125], v199 offset:32768
	ds_read_b128 v[134:137], v199 offset:33792
	ds_read_b128 v[138:141], v199 offset:34816
	ds_read_b128 v[142:145], v199 offset:35840
	ds_read_b128 v[146:149], v199 offset:49152
	ds_read_b128 v[150:153], v199 offset:50176
	ds_read_b128 v[154:157], v199 offset:51200
	ds_read_b128 v[182:185], v199 offset:52224
	s_add_i32 s54, 0, 0x18000
	s_add_i32 s55, 0, 0x1c000
	s_add_u32 s22, s28, 0x160000
	s_addc_u32 s23, s29, 0
	s_mov_b32 m0, s48
	ds_read_b128 v[186:189], v202 offset:32768
	ds_read_b128 v[190:193], v202 offset:33792
	ds_read_b128 v[194:197], v202 offset:34816
	ds_read_b128 v[218:221], v202 offset:35840
	ds_read_b128 v[222:225], v202 offset:36864
	ds_read_b128 v[226:229], v202 offset:37888
	ds_read_b128 v[230:233], v202 offset:38912
	ds_read_b128 v[234:237], v202 offset:39936
	global_load_lds_dwordx4 v162, s[22:23]
	s_mov_b32 m0, s49
	s_nop 0
	global_load_lds_dwordx4 v160, s[22:23]
	s_waitcnt vmcnt(8)
	s_waitcnt lgkmcnt(0)
	s_barrier
	v_mfma_f32_16x16x32_bf16 v[130:133], v[122:125], v[186:189], v[130:133]
	v_mfma_f32_16x16x32_bf16 v[126:129], v[138:141], v[186:189], v[126:129]
	v_mfma_f32_16x16x32_bf16 v[110:113], v[122:125], v[194:197], v[110:113]
	v_mfma_f32_16x16x32_bf16 v[106:109], v[138:141], v[194:197], v[106:109]
	v_mfma_f32_16x16x32_bf16 v[94:97], v[122:125], v[222:225], v[94:97]
	v_mfma_f32_16x16x32_bf16 v[90:93], v[138:141], v[222:225], v[90:93]
	v_mfma_f32_16x16x32_bf16 v[78:81], v[122:125], v[230:233], v[78:81]
	v_mfma_f32_16x16x32_bf16 v[74:77], v[138:141], v[230:233], v[74:77]
	v_mfma_f32_16x16x32_bf16 v[130:133], v[134:137], v[190:193], v[130:133]
	v_mfma_f32_16x16x32_bf16 v[126:129], v[142:145], v[190:193], v[126:129]
	v_mfma_f32_16x16x32_bf16 v[110:113], v[134:137], v[218:221], v[110:113]
	v_mfma_f32_16x16x32_bf16 v[106:109], v[142:145], v[218:221], v[106:109]
	v_mfma_f32_16x16x32_bf16 v[94:97], v[134:137], v[226:229], v[94:97]
	v_mfma_f32_16x16x32_bf16 v[90:93], v[142:145], v[226:229], v[90:93]
	v_mfma_f32_16x16x32_bf16 v[78:81], v[134:137], v[234:237], v[78:81]
	v_mfma_f32_16x16x32_bf16 v[74:77], v[142:145], v[234:237], v[74:77]
	v_mfma_f32_16x16x32_bf16 v[118:121], v[146:149], v[186:189], v[118:121]
	v_mfma_f32_16x16x32_bf16 v[114:117], v[154:157], v[186:189], v[114:117]
	v_mfma_f32_16x16x32_bf16 v[102:105], v[146:149], v[194:197], v[102:105]
	v_mfma_f32_16x16x32_bf16 v[98:101], v[154:157], v[194:197], v[98:101]
	v_mfma_f32_16x16x32_bf16 v[86:89], v[146:149], v[222:225], v[86:89]
	v_mfma_f32_16x16x32_bf16 v[82:85], v[154:157], v[222:225], v[82:85]
	v_mfma_f32_16x16x32_bf16 v[70:73], v[146:149], v[230:233], v[70:73]
	v_mfma_f32_16x16x32_bf16 v[66:69], v[154:157], v[230:233], v[66:69]
	v_mfma_f32_16x16x32_bf16 v[118:121], v[150:153], v[190:193], v[118:121]
	v_mfma_f32_16x16x32_bf16 v[114:117], v[182:185], v[190:193], v[114:117]
	v_mfma_f32_16x16x32_bf16 v[102:105], v[150:153], v[218:221], v[102:105]
	v_mfma_f32_16x16x32_bf16 v[98:101], v[182:185], v[218:221], v[98:101]
	v_mfma_f32_16x16x32_bf16 v[86:89], v[150:153], v[226:229], v[86:89]
	v_mfma_f32_16x16x32_bf16 v[82:85], v[182:185], v[226:229], v[82:85]
	v_mfma_f32_16x16x32_bf16 v[70:73], v[150:153], v[234:237], v[70:73]
	v_mfma_f32_16x16x32_bf16 v[66:69], v[182:185], v[234:237], v[66:69]
	s_barrier
	ds_read_b128 v[186:189], v202 offset:49152
	ds_read_b128 v[190:193], v202 offset:50176
	ds_read_b128 v[194:197], v202 offset:51200
	ds_read_b128 v[218:221], v202 offset:52224
	ds_read_b128 v[222:225], v202 offset:53248
	ds_read_b128 v[226:229], v202 offset:54272
	ds_read_b128 v[230:233], v202 offset:55296
	ds_read_b128 v[234:237], v202 offset:56320
	s_add_i32 s22, s54, s2
	s_add_i32 m0, s22, 0xffffff80
	s_nop 0
	global_load_lds_dwordx4 v0, s[26:27] offset:128
	s_add_i32 m0, s22, 0x2000
	s_add_u32 s22, s26, 0x160080
	v_lshl_add_u64 v[238:239], v[240:241], 0, s[34:35]
	s_addc_u32 s23, s27, 0
	s_add_i32 s26, s55, s2
	global_load_lds_dwordx4 v[238:239], off
	s_mov_b32 m0, s26
	s_nop 0
	global_load_lds_dwordx4 v0, s[22:23]
	s_add_i32 m0, s26, 0x2000
	s_nop 0
	global_load_lds_dwordx4 v158, s[22:23]
	s_add_i32 m0, s51, 0xffffff80
	s_nop 0
	global_load_lds_dwordx4 v162, s[28:29] offset:128
	s_add_i32 m0, s52, 0xffffff80
	s_nop 0
	global_load_lds_dwordx4 v160, s[28:29] offset:128
	s_waitcnt vmcnt(8)
	s_waitcnt lgkmcnt(0)
	s_barrier
	v_mfma_f32_16x16x32_bf16 v[62:65], v[122:125], v[186:189], v[62:65]
	v_mfma_f32_16x16x32_bf16 v[58:61], v[138:141], v[186:189], v[58:61]
	v_mfma_f32_16x16x32_bf16 v[46:49], v[122:125], v[194:197], v[46:49]
	v_mfma_f32_16x16x32_bf16 v[42:45], v[138:141], v[194:197], v[42:45]
	v_mfma_f32_16x16x32_bf16 v[30:33], v[122:125], v[222:225], v[30:33]
	v_mfma_f32_16x16x32_bf16 v[26:29], v[138:141], v[222:225], v[26:29]
	v_mfma_f32_16x16x32_bf16 v[14:17], v[122:125], v[230:233], v[14:17]
	v_mfma_f32_16x16x32_bf16 v[10:13], v[138:141], v[230:233], v[10:13]
	v_mfma_f32_16x16x32_bf16 v[62:65], v[134:137], v[190:193], v[62:65]
	v_mfma_f32_16x16x32_bf16 v[58:61], v[142:145], v[190:193], v[58:61]
	v_mfma_f32_16x16x32_bf16 v[46:49], v[134:137], v[218:221], v[46:49]
	v_mfma_f32_16x16x32_bf16 v[42:45], v[142:145], v[218:221], v[42:45]
	v_mfma_f32_16x16x32_bf16 v[30:33], v[134:137], v[226:229], v[30:33]
	v_mfma_f32_16x16x32_bf16 v[26:29], v[142:145], v[226:229], v[26:29]
	v_mfma_f32_16x16x32_bf16 v[14:17], v[134:137], v[234:237], v[14:17]
	v_mfma_f32_16x16x32_bf16 v[10:13], v[142:145], v[234:237], v[10:13]
	v_mfma_f32_16x16x32_bf16 v[54:57], v[146:149], v[186:189], v[54:57]
	v_mfma_f32_16x16x32_bf16 v[50:53], v[154:157], v[186:189], v[50:53]
	v_mfma_f32_16x16x32_bf16 v[38:41], v[146:149], v[194:197], v[38:41]
	v_mfma_f32_16x16x32_bf16 v[34:37], v[154:157], v[194:197], v[34:37]
	v_mfma_f32_16x16x32_bf16 v[22:25], v[146:149], v[222:225], v[22:25]
	v_mfma_f32_16x16x32_bf16 v[18:21], v[154:157], v[222:225], v[18:21]
	v_mfma_f32_16x16x32_bf16 v[6:9], v[146:149], v[230:233], v[6:9]
	v_mfma_f32_16x16x32_bf16 v[2:5], v[154:157], v[230:233], v[2:5]
	v_mfma_f32_16x16x32_bf16 v[54:57], v[150:153], v[190:193], v[54:57]
	v_mfma_f32_16x16x32_bf16 v[50:53], v[182:185], v[190:193], v[50:53]
	v_mfma_f32_16x16x32_bf16 v[38:41], v[150:153], v[218:221], v[38:41]
	s_add_i32 s78, s78, 2
	v_mfma_f32_16x16x32_bf16 v[34:37], v[182:185], v[218:221], v[34:37]
	s_add_u32 s44, s44, 0x100
	v_mfma_f32_16x16x32_bf16 v[22:25], v[150:153], v[226:229], v[22:25]
	s_addc_u32 s45, s45, 0
	v_mfma_f32_16x16x32_bf16 v[18:21], v[182:185], v[226:229], v[18:21]
	s_mov_b64 s[22:23], s[24:25]
	v_mfma_f32_16x16x32_bf16 v[6:9], v[150:153], v[234:237], v[6:9]
	v_mfma_f32_16x16x32_bf16 v[2:5], v[182:185], v[234:237], v[2:5]
	s_barrier
	s_cmpk_gt_u32 s78, 0x55
	s_cbranch_scc0 .LBB0_802
	s_and_b64 vcc, exec, s[6:7]
	s_cbranch_vccz .LBB0_805
	s_barrier
